# P2 epilogues: row scale num/sqrt(x) by v_rsq_f32 (was correctly-rounded sqrt + IEEE divide, 35 VALU x 8 per thread per tile); gelu argument's two constant multiplies fused into one
# speedup vs baseline: 1.0017x; 1.0017x over previous
; __device__ __forceinline__ u32x4 pack8(const f32x4 a, const f32x4 b) { u32x4 w; w.x = cvt_pk_bf16(a[0], a[1]); w.y = cvt_pk_bf16(a[2], a[3]); w.z = cvt_pk_bf16(b[0], b[1]); w.w = cvt_pk_bf16(b[2], b[3]); return w; }
;     __device__ __forceinline__ void operator()(const f32x4 (&acc)[2][2][4][2], const Unit& u, int wr, int wc, int fr, int fq) const {
;     ...
;             for (int m = 0; m < 4; ++m) { const int row = row0 + ai * HALF + m * 16;
;                 float s;
;                 if (nslot == 8) { const f32x4 a = *(const f32x4*)(ssq + (size_t)row * 8), b = *(const f32x4*)(ssq + (size_t)row * 8 + 4); s = ((a[0] + a[1]) + (a[2] + a[3])) + ((b[0] + b[1]) + (b[2] + b[3])); }
;                 else { const f32x4 a = *(const f32x4*)(ssq + (size_t)row * 4); s = (a[0] + a[1]) + (a[2] + a[3]); }
;                 const float rs = oscale / sqrtf(s * invK + EPS);
;                 f32x4 csA = {1.f, 0.f, 1.f, 0.f}, csB = {1.f, 0.f, 1.f, 0.f};
;                 if (dorope) { const int pos = row & (SEQ - 1); const float* cs = rope + ((size_t)pos * 32 + 16 * (wc & 1) + 4 * fq) * 2; csA = *(const f32x4*)cs; csB = *(const f32x4*)(cs + 4); }
; #pragma unroll
;                 for (int bj = 0; bj < 2; ++bj) { f32x4 v0 = acc[ai][bj][m][0] * rs, v1 = acc[ai][bj][m][1] * rs;
;                     if (dorope) rope8(v0, v1, csA, csB);
;                     *(u32x4*)(base + (size_t)row * ld + bj * HALF + cw) = pack8(v0, v1); } }
.LBB0_204:
	s_waitcnt vmcnt(0)
	v_add_f32_e32 v142, v142, v143
	v_add_f32_e32 v143, v144, v145
	v_add_f32_e32 v138, v138, v139
	v_add_f32_e32 v139, v140, v141
	v_add_f32_e32 v142, v142, v143
	v_add_f32_e32 v138, v138, v139
	v_add_f32_e32 v138, v142, v138
	v_fmamk_f32 v138, v138, 0x3b000000, v182
	v_rsq_f32_e32 v140, v138
	s_nop 0
	v_mul_f32_e32 v140, s63, v140
	v_pk_mul_f32 v[142:143], v[128:129], v[140:141] op_sel_hi:[1,0]
	v_pk_mul_f32 v[128:129], v[124:125], v[140:141] op_sel_hi:[1,0]
	v_cndmask_b32_e64 v124, 0, 1, s[84:85]
	v_pk_mul_f32 v[126:127], v[126:127], v[140:141] op_sel_hi:[1,0]
	v_cmp_ne_u32_e64 s[4:5], 1, v124
	s_andn2_b64 vcc, exec, s[84:85]
	v_pk_mul_f32 v[124:125], v[122:123], v[140:141] op_sel_hi:[1,0]
	s_cbranch_vccnz .LBB0_206
	v_pk_mul_f32 v[138:139], v[126:127], v[134:135] op_sel:[1,1] op_sel_hi:[0,1]
	v_pk_mul_f32 v[122:123], v[126:127], v[134:135]
	v_pk_fma_f32 v[126:127], v[126:127], v[134:135], v[138:139] op_sel_hi:[1,0,1]
	v_pk_mul_f32 v[186:187], v[124:125], v[130:131] op_sel:[1,1] op_sel_hi:[0,1]
	v_mul_f32_e32 v126, v143, v137
	v_pk_fma_f32 v[144:145], v[142:143], v[136:137], v[126:127] op_sel_hi:[1,1,0] neg_lo:[0,0,1] neg_hi:[0,0,1]
	v_mul_f32_e32 v126, v142, v137
	v_pk_fma_f32 v[184:185], v[142:143], v[136:137], v[126:127] op_sel:[1,0,0] op_sel_hi:[0,1,0]
	v_pk_mul_f32 v[142:143], v[124:125], v[130:131]
	v_pk_fma_f32 v[124:125], v[124:125], v[130:131], v[186:187] op_sel_hi:[1,0,1]
	v_sub_f32_e32 v126, v122, v138
	v_mul_f32_e32 v124, v129, v133
	v_pk_fma_f32 v[188:189], v[128:129], v[132:133], v[124:125] op_sel_hi:[1,1,0] neg_lo:[0,0,1] neg_hi:[0,0,1]
	v_mul_f32_e32 v124, v128, v133
	v_pk_fma_f32 v[190:191], v[128:129], v[132:133], v[124:125] op_sel:[1,0,0] op_sel_hi:[0,1,0]
	v_sub_f32_e32 v124, v142, v186
	v_mov_b32_e32 v128, v188
	v_mov_b32_e32 v129, v190
	v_mov_b32_e32 v142, v144
	v_mov_b32_e32 v143, v184

; __device__ __forceinline__ u32x4 pack8(const f32x4 a, const f32x4 b) { u32x4 w; w.x = cvt_pk_bf16(a[0], a[1]); w.y = cvt_pk_bf16(a[2], a[3]); w.z = cvt_pk_bf16(b[0], b[1]); w.w = cvt_pk_bf16(b[2], b[3]); return w; }
;     __device__ __forceinline__ void operator()(const f32x4 (&acc)[2][2][4][2], const Unit& u, int wr, int wc, int fr, int fq) const {
;     ...
;             for (int m = 0; m < 4; ++m) { const int row = row0 + ai * HALF + m * 16;
;                 float s;
;                 if (nslot == 8) { const f32x4 a = *(const f32x4*)(ssq + (size_t)row * 8), b = *(const f32x4*)(ssq + (size_t)row * 8 + 4); s = ((a[0] + a[1]) + (a[2] + a[3])) + ((b[0] + b[1]) + (b[2] + b[3])); }
;                 else { const f32x4 a = *(const f32x4*)(ssq + (size_t)row * 4); s = (a[0] + a[1]) + (a[2] + a[3]); }
;                 const float rs = oscale / sqrtf(s * invK + EPS);
;                 f32x4 csA = {1.f, 0.f, 1.f, 0.f}, csB = {1.f, 0.f, 1.f, 0.f};
;                 if (dorope) { const int pos = row & (SEQ - 1); const float* cs = rope + ((size_t)pos * 32 + 16 * (wc & 1) + 4 * fq) * 2; csA = *(const f32x4*)cs; csB = *(const f32x4*)(cs + 4); }
; #pragma unroll
;                 for (int bj = 0; bj < 2; ++bj) { f32x4 v0 = acc[ai][bj][m][0] * rs, v1 = acc[ai][bj][m][1] * rs;
;                     if (dorope) rope8(v0, v1, csA, csB);
;                     *(u32x4*)(base + (size_t)row * ld + bj * HALF + cw) = pack8(v0, v1); } }
.LBB0_211:
	s_waitcnt vmcnt(0)
	v_add_f32_e32 v126, v126, v127
	v_add_f32_e32 v127, v128, v129
	v_add_f32_e32 v122, v122, v123
	v_add_f32_e32 v123, v124, v125
	v_add_f32_e32 v126, v126, v127
	v_add_f32_e32 v122, v122, v123
	v_add_f32_e32 v122, v126, v122
	v_fmamk_f32 v122, v122, 0x3b000000, v182
	v_rsq_f32_e32 v122, v122
	s_nop 0
	v_mul_f32_e32 v122, s63, v122
	v_pk_mul_f32 v[124:125], v[112:113], v[122:123] op_sel_hi:[1,0]
	v_pk_mul_f32 v[110:111], v[110:111], v[122:123] op_sel_hi:[1,0]
	v_pk_mul_f32 v[112:113], v[108:109], v[122:123] op_sel_hi:[1,0]
	s_and_b64 vcc, exec, s[4:5]
	v_pk_mul_f32 v[108:109], v[106:107], v[122:123] op_sel_hi:[1,0]
	s_cbranch_vccnz .LBB0_213
	v_pk_mul_f32 v[126:127], v[110:111], v[118:119] op_sel:[1,1] op_sel_hi:[0,1]
	v_pk_mul_f32 v[106:107], v[110:111], v[118:119]
	v_pk_fma_f32 v[110:111], v[110:111], v[118:119], v[126:127] op_sel_hi:[1,0,1]
	v_pk_mul_f32 v[134:135], v[108:109], v[114:115] op_sel:[1,1] op_sel_hi:[0,1]
	v_mul_f32_e32 v110, v125, v121
	v_pk_fma_f32 v[128:129], v[124:125], v[120:121], v[110:111] op_sel_hi:[1,1,0] neg_lo:[0,0,1] neg_hi:[0,0,1]
	v_mul_f32_e32 v110, v124, v121
	v_pk_fma_f32 v[132:133], v[124:125], v[120:121], v[110:111] op_sel:[1,0,0] op_sel_hi:[0,1,0]
	v_pk_mul_f32 v[124:125], v[108:109], v[114:115]
	v_pk_fma_f32 v[108:109], v[108:109], v[114:115], v[134:135] op_sel_hi:[1,0,1]
	v_sub_f32_e32 v110, v106, v126
	v_mul_f32_e32 v108, v113, v117
	v_pk_fma_f32 v[136:137], v[112:113], v[116:117], v[108:109] op_sel_hi:[1,1,0] neg_lo:[0,0,1] neg_hi:[0,0,1]
	v_mul_f32_e32 v108, v112, v117
	v_pk_fma_f32 v[140:141], v[112:113], v[116:117], v[108:109] op_sel:[1,0,0] op_sel_hi:[0,1,0]
	v_sub_f32_e32 v108, v124, v134
	v_mov_b32_e32 v112, v136
	v_mov_b32_e32 v113, v140
	v_mov_b32_e32 v124, v128
	v_mov_b32_e32 v125, v132

; __device__ __forceinline__ u32x4 pack8(const f32x4 a, const f32x4 b) { u32x4 w; w.x = cvt_pk_bf16(a[0], a[1]); w.y = cvt_pk_bf16(a[2], a[3]); w.z = cvt_pk_bf16(b[0], b[1]); w.w = cvt_pk_bf16(b[2], b[3]); return w; }
;     __device__ __forceinline__ void operator()(const f32x4 (&acc)[2][2][4][2], const Unit& u, int wr, int wc, int fr, int fq) const {
;     ...
;             for (int m = 0; m < 4; ++m) { const int row = row0 + ai * HALF + m * 16;
;                 float s;
;                 if (nslot == 8) { const f32x4 a = *(const f32x4*)(ssq + (size_t)row * 8), b = *(const f32x4*)(ssq + (size_t)row * 8 + 4); s = ((a[0] + a[1]) + (a[2] + a[3])) + ((b[0] + b[1]) + (b[2] + b[3])); }
;                 else { const f32x4 a = *(const f32x4*)(ssq + (size_t)row * 4); s = (a[0] + a[1]) + (a[2] + a[3]); }
;                 const float rs = oscale / sqrtf(s * invK + EPS);
;                 f32x4 csA = {1.f, 0.f, 1.f, 0.f}, csB = {1.f, 0.f, 1.f, 0.f};
;                 if (dorope) { const int pos = row & (SEQ - 1); const float* cs = rope + ((size_t)pos * 32 + 16 * (wc & 1) + 4 * fq) * 2; csA = *(const f32x4*)cs; csB = *(const f32x4*)(cs + 4); }
; #pragma unroll
;                 for (int bj = 0; bj < 2; ++bj) { f32x4 v0 = acc[ai][bj][m][0] * rs, v1 = acc[ai][bj][m][1] * rs;
;                     if (dorope) rope8(v0, v1, csA, csB);
;                     *(u32x4*)(base + (size_t)row * ld + bj * HALF + cw) = pack8(v0, v1); } }
.LBB0_218:
	s_waitcnt vmcnt(0)
	v_add_f32_e32 v110, v110, v111
	v_add_f32_e32 v111, v112, v113
	v_add_f32_e32 v106, v106, v107
	v_add_f32_e32 v107, v108, v109
	v_add_f32_e32 v110, v110, v111
	v_add_f32_e32 v106, v106, v107
	v_add_f32_e32 v106, v110, v106
	v_fmamk_f32 v106, v106, 0x3b000000, v182
	v_rsq_f32_e32 v106, v106
	s_nop 0
	v_mul_f32_e32 v106, s63, v106
	v_pk_mul_f32 v[108:109], v[96:97], v[106:107] op_sel_hi:[1,0]
	v_pk_mul_f32 v[94:95], v[94:95], v[106:107] op_sel_hi:[1,0]
	v_pk_mul_f32 v[96:97], v[92:93], v[106:107] op_sel_hi:[1,0]
	s_and_b64 vcc, exec, s[4:5]
	v_pk_mul_f32 v[92:93], v[90:91], v[106:107] op_sel_hi:[1,0]
	s_cbranch_vccnz .LBB0_220
	v_pk_mul_f32 v[110:111], v[94:95], v[102:103] op_sel:[1,1] op_sel_hi:[0,1]
	v_pk_mul_f32 v[90:91], v[94:95], v[102:103]
	v_pk_fma_f32 v[94:95], v[94:95], v[102:103], v[110:111] op_sel_hi:[1,0,1]
	v_pk_mul_f32 v[118:119], v[92:93], v[98:99] op_sel:[1,1] op_sel_hi:[0,1]
	v_mul_f32_e32 v94, v109, v105
	v_pk_fma_f32 v[112:113], v[108:109], v[104:105], v[94:95] op_sel_hi:[1,1,0] neg_lo:[0,0,1] neg_hi:[0,0,1]
	v_mul_f32_e32 v94, v108, v105
	v_pk_fma_f32 v[116:117], v[108:109], v[104:105], v[94:95] op_sel:[1,0,0] op_sel_hi:[0,1,0]
	v_pk_mul_f32 v[108:109], v[92:93], v[98:99]
	v_pk_fma_f32 v[92:93], v[92:93], v[98:99], v[118:119] op_sel_hi:[1,0,1]
	v_sub_f32_e32 v94, v90, v110
	v_mul_f32_e32 v92, v97, v101
	v_pk_fma_f32 v[120:121], v[96:97], v[100:101], v[92:93] op_sel_hi:[1,1,0] neg_lo:[0,0,1] neg_hi:[0,0,1]
	v_mul_f32_e32 v92, v96, v101
	v_pk_fma_f32 v[122:123], v[96:97], v[100:101], v[92:93] op_sel:[1,0,0] op_sel_hi:[0,1,0]
	v_sub_f32_e32 v92, v108, v118
	v_mov_b32_e32 v96, v120
	v_mov_b32_e32 v97, v122
	v_mov_b32_e32 v108, v112
	v_mov_b32_e32 v109, v116

; __device__ __forceinline__ u32x4 pack8(const f32x4 a, const f32x4 b) { u32x4 w; w.x = cvt_pk_bf16(a[0], a[1]); w.y = cvt_pk_bf16(a[2], a[3]); w.z = cvt_pk_bf16(b[0], b[1]); w.w = cvt_pk_bf16(b[2], b[3]); return w; }
;     __device__ __forceinline__ void operator()(const f32x4 (&acc)[2][2][4][2], const Unit& u, int wr, int wc, int fr, int fq) const {
;     ...
;             for (int m = 0; m < 4; ++m) { const int row = row0 + ai * HALF + m * 16;
;                 float s;
;                 if (nslot == 8) { const f32x4 a = *(const f32x4*)(ssq + (size_t)row * 8), b = *(const f32x4*)(ssq + (size_t)row * 8 + 4); s = ((a[0] + a[1]) + (a[2] + a[3])) + ((b[0] + b[1]) + (b[2] + b[3])); }
;                 else { const f32x4 a = *(const f32x4*)(ssq + (size_t)row * 4); s = (a[0] + a[1]) + (a[2] + a[3]); }
;                 const float rs = oscale / sqrtf(s * invK + EPS);
;                 f32x4 csA = {1.f, 0.f, 1.f, 0.f}, csB = {1.f, 0.f, 1.f, 0.f};
;                 if (dorope) { const int pos = row & (SEQ - 1); const float* cs = rope + ((size_t)pos * 32 + 16 * (wc & 1) + 4 * fq) * 2; csA = *(const f32x4*)cs; csB = *(const f32x4*)(cs + 4); }
; #pragma unroll
;                 for (int bj = 0; bj < 2; ++bj) { f32x4 v0 = acc[ai][bj][m][0] * rs, v1 = acc[ai][bj][m][1] * rs;
;                     if (dorope) rope8(v0, v1, csA, csB);
;                     *(u32x4*)(base + (size_t)row * ld + bj * HALF + cw) = pack8(v0, v1); } }
.LBB0_225:
	s_waitcnt vmcnt(0)
	v_add_f32_e32 v94, v94, v95
	v_add_f32_e32 v95, v96, v97
	v_add_f32_e32 v90, v90, v91
	v_add_f32_e32 v91, v92, v93
	v_add_f32_e32 v94, v94, v95
	v_add_f32_e32 v90, v90, v91
	v_add_f32_e32 v90, v94, v90
	v_fmamk_f32 v90, v90, 0x3b000000, v182
	v_rsq_f32_e32 v90, v90
	s_nop 0
	v_mul_f32_e32 v90, s63, v90
	v_pk_mul_f32 v[92:93], v[80:81], v[90:91] op_sel_hi:[1,0]
	v_pk_mul_f32 v[78:79], v[78:79], v[90:91] op_sel_hi:[1,0]
	v_pk_mul_f32 v[80:81], v[76:77], v[90:91] op_sel_hi:[1,0]
	s_and_b64 vcc, exec, s[4:5]
	v_pk_mul_f32 v[76:77], v[74:75], v[90:91] op_sel_hi:[1,0]
	s_cbranch_vccnz .LBB0_227
	v_pk_mul_f32 v[94:95], v[78:79], v[86:87] op_sel:[1,1] op_sel_hi:[0,1]
	v_pk_mul_f32 v[74:75], v[78:79], v[86:87]
	v_pk_fma_f32 v[78:79], v[78:79], v[86:87], v[94:95] op_sel_hi:[1,0,1]
	v_pk_mul_f32 v[102:103], v[76:77], v[82:83] op_sel:[1,1] op_sel_hi:[0,1]
	v_mul_f32_e32 v78, v93, v89
	v_pk_fma_f32 v[96:97], v[92:93], v[88:89], v[78:79] op_sel_hi:[1,1,0] neg_lo:[0,0,1] neg_hi:[0,0,1]
	v_mul_f32_e32 v78, v92, v89
	v_pk_fma_f32 v[100:101], v[92:93], v[88:89], v[78:79] op_sel:[1,0,0] op_sel_hi:[0,1,0]
	v_pk_mul_f32 v[92:93], v[76:77], v[82:83]
	v_pk_fma_f32 v[76:77], v[76:77], v[82:83], v[102:103] op_sel_hi:[1,0,1]
	v_sub_f32_e32 v78, v74, v94
	v_mul_f32_e32 v76, v81, v85
	v_pk_fma_f32 v[104:105], v[80:81], v[84:85], v[76:77] op_sel_hi:[1,1,0] neg_lo:[0,0,1] neg_hi:[0,0,1]
	v_mul_f32_e32 v76, v80, v85
	v_pk_fma_f32 v[106:107], v[80:81], v[84:85], v[76:77] op_sel:[1,0,0] op_sel_hi:[0,1,0]
	v_sub_f32_e32 v76, v92, v102
	v_mov_b32_e32 v80, v104
	v_mov_b32_e32 v81, v106
	v_mov_b32_e32 v92, v96
	v_mov_b32_e32 v93, v100

; __device__ __forceinline__ u32x4 pack8(const f32x4 a, const f32x4 b) { u32x4 w; w.x = cvt_pk_bf16(a[0], a[1]); w.y = cvt_pk_bf16(a[2], a[3]); w.z = cvt_pk_bf16(b[0], b[1]); w.w = cvt_pk_bf16(b[2], b[3]); return w; }
;     __device__ __forceinline__ void operator()(const f32x4 (&acc)[2][2][4][2], const Unit& u, int wr, int wc, int fr, int fq) const {
;     ...
;             for (int m = 0; m < 4; ++m) { const int row = row0 + ai * HALF + m * 16;
;                 float s;
;                 if (nslot == 8) { const f32x4 a = *(const f32x4*)(ssq + (size_t)row * 8), b = *(const f32x4*)(ssq + (size_t)row * 8 + 4); s = ((a[0] + a[1]) + (a[2] + a[3])) + ((b[0] + b[1]) + (b[2] + b[3])); }
;                 else { const f32x4 a = *(const f32x4*)(ssq + (size_t)row * 4); s = (a[0] + a[1]) + (a[2] + a[3]); }
;                 const float rs = oscale / sqrtf(s * invK + EPS);
;                 f32x4 csA = {1.f, 0.f, 1.f, 0.f}, csB = {1.f, 0.f, 1.f, 0.f};
;                 if (dorope) { const int pos = row & (SEQ - 1); const float* cs = rope + ((size_t)pos * 32 + 16 * (wc & 1) + 4 * fq) * 2; csA = *(const f32x4*)cs; csB = *(const f32x4*)(cs + 4); }
; #pragma unroll
;                 for (int bj = 0; bj < 2; ++bj) { f32x4 v0 = acc[ai][bj][m][0] * rs, v1 = acc[ai][bj][m][1] * rs;
;                     if (dorope) rope8(v0, v1, csA, csB);
;                     *(u32x4*)(base + (size_t)row * ld + bj * HALF + cw) = pack8(v0, v1); } }
.LBB0_232:
	s_waitcnt vmcnt(0)
	v_add_f32_e32 v78, v78, v79
	v_add_f32_e32 v79, v80, v81
	v_add_f32_e32 v74, v74, v75
	v_add_f32_e32 v75, v76, v77
	v_add_f32_e32 v78, v78, v79
	v_add_f32_e32 v74, v74, v75
	v_add_f32_e32 v74, v78, v74
	v_fmamk_f32 v74, v74, 0x3b000000, v182
	v_rsq_f32_e32 v74, v74
	s_nop 0
	v_mul_f32_e32 v74, s63, v74
	v_pk_mul_f32 v[76:77], v[64:65], v[74:75] op_sel_hi:[1,0]
	v_pk_mul_f32 v[62:63], v[62:63], v[74:75] op_sel_hi:[1,0]
	v_pk_mul_f32 v[64:65], v[60:61], v[74:75] op_sel_hi:[1,0]
	s_and_b64 vcc, exec, s[4:5]
	v_pk_mul_f32 v[60:61], v[58:59], v[74:75] op_sel_hi:[1,0]
	s_cbranch_vccnz .LBB0_234
	v_pk_mul_f32 v[78:79], v[62:63], v[70:71] op_sel:[1,1] op_sel_hi:[0,1]
	v_pk_mul_f32 v[58:59], v[62:63], v[70:71]
	v_pk_fma_f32 v[62:63], v[62:63], v[70:71], v[78:79] op_sel_hi:[1,0,1]
	v_pk_mul_f32 v[86:87], v[60:61], v[66:67] op_sel:[1,1] op_sel_hi:[0,1]
	v_mul_f32_e32 v62, v77, v73
	v_pk_fma_f32 v[80:81], v[76:77], v[72:73], v[62:63] op_sel_hi:[1,1,0] neg_lo:[0,0,1] neg_hi:[0,0,1]
	v_mul_f32_e32 v62, v76, v73
	v_pk_fma_f32 v[84:85], v[76:77], v[72:73], v[62:63] op_sel:[1,0,0] op_sel_hi:[0,1,0]
	v_pk_mul_f32 v[76:77], v[60:61], v[66:67]
	v_pk_fma_f32 v[60:61], v[60:61], v[66:67], v[86:87] op_sel_hi:[1,0,1]
	v_sub_f32_e32 v62, v58, v78
	v_mul_f32_e32 v60, v65, v69
	v_pk_fma_f32 v[88:89], v[64:65], v[68:69], v[60:61] op_sel_hi:[1,1,0] neg_lo:[0,0,1] neg_hi:[0,0,1]
	v_mul_f32_e32 v60, v64, v69
	v_pk_fma_f32 v[90:91], v[64:65], v[68:69], v[60:61] op_sel:[1,0,0] op_sel_hi:[0,1,0]
	v_sub_f32_e32 v60, v76, v86
	v_mov_b32_e32 v64, v88
	v_mov_b32_e32 v65, v90
	v_mov_b32_e32 v76, v80
	v_mov_b32_e32 v77, v84

; __device__ __forceinline__ u32x4 pack8(const f32x4 a, const f32x4 b) { u32x4 w; w.x = cvt_pk_bf16(a[0], a[1]); w.y = cvt_pk_bf16(a[2], a[3]); w.z = cvt_pk_bf16(b[0], b[1]); w.w = cvt_pk_bf16(b[2], b[3]); return w; }
;     __device__ __forceinline__ void operator()(const f32x4 (&acc)[2][2][4][2], const Unit& u, int wr, int wc, int fr, int fq) const {
;     ...
;             for (int m = 0; m < 4; ++m) { const int row = row0 + ai * HALF + m * 16;
;                 float s;
;                 if (nslot == 8) { const f32x4 a = *(const f32x4*)(ssq + (size_t)row * 8), b = *(const f32x4*)(ssq + (size_t)row * 8 + 4); s = ((a[0] + a[1]) + (a[2] + a[3])) + ((b[0] + b[1]) + (b[2] + b[3])); }
;                 else { const f32x4 a = *(const f32x4*)(ssq + (size_t)row * 4); s = (a[0] + a[1]) + (a[2] + a[3]); }
;                 const float rs = oscale / sqrtf(s * invK + EPS);
;                 f32x4 csA = {1.f, 0.f, 1.f, 0.f}, csB = {1.f, 0.f, 1.f, 0.f};
;                 if (dorope) { const int pos = row & (SEQ - 1); const float* cs = rope + ((size_t)pos * 32 + 16 * (wc & 1) + 4 * fq) * 2; csA = *(const f32x4*)cs; csB = *(const f32x4*)(cs + 4); }
; #pragma unroll
;                 for (int bj = 0; bj < 2; ++bj) { f32x4 v0 = acc[ai][bj][m][0] * rs, v1 = acc[ai][bj][m][1] * rs;
;                     if (dorope) rope8(v0, v1, csA, csB);
;                     *(u32x4*)(base + (size_t)row * ld + bj * HALF + cw) = pack8(v0, v1); } }
.LBB0_239:
	s_waitcnt vmcnt(0)
	v_add_f32_e32 v62, v62, v63
	v_add_f32_e32 v63, v64, v65
	v_add_f32_e32 v58, v58, v59
	v_add_f32_e32 v59, v60, v61
	v_add_f32_e32 v62, v62, v63
	v_add_f32_e32 v58, v58, v59
	v_add_f32_e32 v58, v62, v58
	v_fmamk_f32 v58, v58, 0x3b000000, v182
	v_rsq_f32_e32 v58, v58
	s_nop 0
	v_mul_f32_e32 v58, s63, v58
	v_pk_mul_f32 v[60:61], v[48:49], v[58:59] op_sel_hi:[1,0]
	v_pk_mul_f32 v[46:47], v[46:47], v[58:59] op_sel_hi:[1,0]
	v_pk_mul_f32 v[48:49], v[44:45], v[58:59] op_sel_hi:[1,0]
	s_and_b64 vcc, exec, s[4:5]
	v_pk_mul_f32 v[44:45], v[42:43], v[58:59] op_sel_hi:[1,0]
	s_cbranch_vccnz .LBB0_241
	v_pk_mul_f32 v[62:63], v[46:47], v[54:55] op_sel:[1,1] op_sel_hi:[0,1]
	v_pk_mul_f32 v[42:43], v[46:47], v[54:55]
	v_pk_fma_f32 v[46:47], v[46:47], v[54:55], v[62:63] op_sel_hi:[1,0,1]
	v_pk_mul_f32 v[70:71], v[44:45], v[50:51] op_sel:[1,1] op_sel_hi:[0,1]
	v_mul_f32_e32 v46, v61, v57
	v_pk_fma_f32 v[64:65], v[60:61], v[56:57], v[46:47] op_sel_hi:[1,1,0] neg_lo:[0,0,1] neg_hi:[0,0,1]
	v_mul_f32_e32 v46, v60, v57
	v_pk_fma_f32 v[68:69], v[60:61], v[56:57], v[46:47] op_sel:[1,0,0] op_sel_hi:[0,1,0]
	v_pk_mul_f32 v[60:61], v[44:45], v[50:51]
	v_pk_fma_f32 v[44:45], v[44:45], v[50:51], v[70:71] op_sel_hi:[1,0,1]
	v_sub_f32_e32 v46, v42, v62
	v_mul_f32_e32 v44, v49, v53
	v_pk_fma_f32 v[72:73], v[48:49], v[52:53], v[44:45] op_sel_hi:[1,1,0] neg_lo:[0,0,1] neg_hi:[0,0,1]
	v_mul_f32_e32 v44, v48, v53
	v_pk_fma_f32 v[74:75], v[48:49], v[52:53], v[44:45] op_sel:[1,0,0] op_sel_hi:[0,1,0]
	v_sub_f32_e32 v44, v60, v70
	v_mov_b32_e32 v48, v72
	v_mov_b32_e32 v49, v74
	v_mov_b32_e32 v60, v64
	v_mov_b32_e32 v61, v68

; __device__ __forceinline__ u32x4 pack8(const f32x4 a, const f32x4 b) { u32x4 w; w.x = cvt_pk_bf16(a[0], a[1]); w.y = cvt_pk_bf16(a[2], a[3]); w.z = cvt_pk_bf16(b[0], b[1]); w.w = cvt_pk_bf16(b[2], b[3]); return w; }
;     __device__ __forceinline__ void operator()(const f32x4 (&acc)[2][2][4][2], const Unit& u, int wr, int wc, int fr, int fq) const {
;     ...
;             for (int m = 0; m < 4; ++m) { const int row = row0 + ai * HALF + m * 16;
;                 float s;
;                 if (nslot == 8) { const f32x4 a = *(const f32x4*)(ssq + (size_t)row * 8), b = *(const f32x4*)(ssq + (size_t)row * 8 + 4); s = ((a[0] + a[1]) + (a[2] + a[3])) + ((b[0] + b[1]) + (b[2] + b[3])); }
;                 else { const f32x4 a = *(const f32x4*)(ssq + (size_t)row * 4); s = (a[0] + a[1]) + (a[2] + a[3]); }
;                 const float rs = oscale / sqrtf(s * invK + EPS);
;                 f32x4 csA = {1.f, 0.f, 1.f, 0.f}, csB = {1.f, 0.f, 1.f, 0.f};
;                 if (dorope) { const int pos = row & (SEQ - 1); const float* cs = rope + ((size_t)pos * 32 + 16 * (wc & 1) + 4 * fq) * 2; csA = *(const f32x4*)cs; csB = *(const f32x4*)(cs + 4); }
; #pragma unroll
;                 for (int bj = 0; bj < 2; ++bj) { f32x4 v0 = acc[ai][bj][m][0] * rs, v1 = acc[ai][bj][m][1] * rs;
;                     if (dorope) rope8(v0, v1, csA, csB);
;                     *(u32x4*)(base + (size_t)row * ld + bj * HALF + cw) = pack8(v0, v1); } }
.LBB0_246:
	s_waitcnt vmcnt(0)
	v_add_f32_e32 v46, v46, v47
	v_add_f32_e32 v47, v48, v49
	v_add_f32_e32 v42, v42, v43
	v_add_f32_e32 v43, v44, v45
	v_add_f32_e32 v46, v46, v47
	v_add_f32_e32 v42, v42, v43
	v_add_f32_e32 v42, v46, v42
	v_fmamk_f32 v42, v42, 0x3b000000, v182
	v_rsq_f32_e32 v42, v42
	s_nop 0
	v_mul_f32_e32 v42, s63, v42
	v_pk_mul_f32 v[44:45], v[32:33], v[42:43] op_sel_hi:[1,0]
	v_pk_mul_f32 v[30:31], v[30:31], v[42:43] op_sel_hi:[1,0]
	v_pk_mul_f32 v[32:33], v[28:29], v[42:43] op_sel_hi:[1,0]
	s_and_b64 vcc, exec, s[4:5]
	v_pk_mul_f32 v[28:29], v[26:27], v[42:43] op_sel_hi:[1,0]
	s_cbranch_vccnz .LBB0_248
	v_pk_mul_f32 v[46:47], v[30:31], v[38:39] op_sel:[1,1] op_sel_hi:[0,1]
	v_pk_mul_f32 v[26:27], v[30:31], v[38:39]
	v_pk_fma_f32 v[30:31], v[30:31], v[38:39], v[46:47] op_sel_hi:[1,0,1]
	v_pk_mul_f32 v[54:55], v[28:29], v[34:35] op_sel:[1,1] op_sel_hi:[0,1]
	v_mul_f32_e32 v30, v45, v41
	v_pk_fma_f32 v[48:49], v[44:45], v[40:41], v[30:31] op_sel_hi:[1,1,0] neg_lo:[0,0,1] neg_hi:[0,0,1]
	v_mul_f32_e32 v30, v44, v41
	v_pk_fma_f32 v[52:53], v[44:45], v[40:41], v[30:31] op_sel:[1,0,0] op_sel_hi:[0,1,0]
	v_pk_mul_f32 v[44:45], v[28:29], v[34:35]
	v_pk_fma_f32 v[28:29], v[28:29], v[34:35], v[54:55] op_sel_hi:[1,0,1]
	v_sub_f32_e32 v30, v26, v46
	v_mul_f32_e32 v28, v33, v37
	v_pk_fma_f32 v[56:57], v[32:33], v[36:37], v[28:29] op_sel_hi:[1,1,0] neg_lo:[0,0,1] neg_hi:[0,0,1]
	v_mul_f32_e32 v28, v32, v37
	v_pk_fma_f32 v[58:59], v[32:33], v[36:37], v[28:29] op_sel:[1,0,0] op_sel_hi:[0,1,0]
	v_sub_f32_e32 v28, v44, v54
	v_mov_b32_e32 v32, v56
	v_mov_b32_e32 v33, v58
	v_mov_b32_e32 v44, v48
	v_mov_b32_e32 v45, v52

; __device__ __forceinline__ u32x4 pack8(const f32x4 a, const f32x4 b) { u32x4 w; w.x = cvt_pk_bf16(a[0], a[1]); w.y = cvt_pk_bf16(a[2], a[3]); w.z = cvt_pk_bf16(b[0], b[1]); w.w = cvt_pk_bf16(b[2], b[3]); return w; }
;     __device__ __forceinline__ void operator()(const f32x4 (&acc)[2][2][4][2], const Unit& u, int wr, int wc, int fr, int fq) const {
;     ...
;             for (int m = 0; m < 4; ++m) { const int row = row0 + ai * HALF + m * 16;
;                 float s;
;                 if (nslot == 8) { const f32x4 a = *(const f32x4*)(ssq + (size_t)row * 8), b = *(const f32x4*)(ssq + (size_t)row * 8 + 4); s = ((a[0] + a[1]) + (a[2] + a[3])) + ((b[0] + b[1]) + (b[2] + b[3])); }
;                 else { const f32x4 a = *(const f32x4*)(ssq + (size_t)row * 4); s = (a[0] + a[1]) + (a[2] + a[3]); }
;                 const float rs = oscale / sqrtf(s * invK + EPS);
;                 f32x4 csA = {1.f, 0.f, 1.f, 0.f}, csB = {1.f, 0.f, 1.f, 0.f};
;                 if (dorope) { const int pos = row & (SEQ - 1); const float* cs = rope + ((size_t)pos * 32 + 16 * (wc & 1) + 4 * fq) * 2; csA = *(const f32x4*)cs; csB = *(const f32x4*)(cs + 4); }
; #pragma unroll
;                 for (int bj = 0; bj < 2; ++bj) { f32x4 v0 = acc[ai][bj][m][0] * rs, v1 = acc[ai][bj][m][1] * rs;
;                     if (dorope) rope8(v0, v1, csA, csB);
;                     *(u32x4*)(base + (size_t)row * ld + bj * HALF + cw) = pack8(v0, v1); } }
.LBB0_253:
	s_waitcnt vmcnt(0)
	v_add_f32_e32 v30, v30, v31
	v_add_f32_e32 v31, v32, v33
	v_add_f32_e32 v26, v26, v27
	v_add_f32_e32 v27, v28, v29
	v_add_f32_e32 v30, v30, v31
	v_add_f32_e32 v26, v26, v27
	v_add_f32_e32 v26, v30, v26
	v_fmamk_f32 v26, v26, 0x3b000000, v182
	v_rsq_f32_e32 v26, v26
	s_nop 0
	v_mul_f32_e32 v26, s63, v26
	v_pk_mul_f32 v[28:29], v[16:17], v[26:27] op_sel_hi:[1,0]
	v_pk_mul_f32 v[14:15], v[14:15], v[26:27] op_sel_hi:[1,0]
	v_pk_mul_f32 v[16:17], v[12:13], v[26:27] op_sel_hi:[1,0]
	s_and_b64 vcc, exec, s[4:5]
	v_pk_mul_f32 v[12:13], v[10:11], v[26:27] op_sel_hi:[1,0]
	s_cbranch_vccnz .LBB0_255
	v_pk_mul_f32 v[30:31], v[14:15], v[22:23] op_sel:[1,1] op_sel_hi:[0,1]
	v_pk_mul_f32 v[10:11], v[14:15], v[22:23]
	v_pk_fma_f32 v[14:15], v[14:15], v[22:23], v[30:31] op_sel_hi:[1,0,1]
	v_pk_mul_f32 v[38:39], v[12:13], v[18:19] op_sel:[1,1] op_sel_hi:[0,1]
	v_mul_f32_e32 v14, v29, v25
	v_pk_fma_f32 v[32:33], v[28:29], v[24:25], v[14:15] op_sel_hi:[1,1,0] neg_lo:[0,0,1] neg_hi:[0,0,1]
	v_mul_f32_e32 v14, v28, v25
	v_pk_fma_f32 v[36:37], v[28:29], v[24:25], v[14:15] op_sel:[1,0,0] op_sel_hi:[0,1,0]
	v_pk_mul_f32 v[28:29], v[12:13], v[18:19]
	v_pk_fma_f32 v[12:13], v[12:13], v[18:19], v[38:39] op_sel_hi:[1,0,1]
	v_sub_f32_e32 v14, v10, v30
	v_mul_f32_e32 v12, v17, v21
	v_pk_fma_f32 v[40:41], v[16:17], v[20:21], v[12:13] op_sel_hi:[1,1,0] neg_lo:[0,0,1] neg_hi:[0,0,1]
	v_mul_f32_e32 v12, v16, v21
	v_pk_fma_f32 v[42:43], v[16:17], v[20:21], v[12:13] op_sel:[1,0,0] op_sel_hi:[0,1,0]
	v_sub_f32_e32 v12, v28, v38
	v_mov_b32_e32 v16, v40
	v_mov_b32_e32 v17, v42
	v_mov_b32_e32 v28, v32
	v_mov_b32_e32 v29, v36

; __device__ __forceinline__ u32x4 pack8(const f32x4 a, const f32x4 b) { u32x4 w; w.x = cvt_pk_bf16(a[0], a[1]); w.y = cvt_pk_bf16(a[2], a[3]); w.z = cvt_pk_bf16(b[0], b[1]); w.w = cvt_pk_bf16(b[2], b[3]); return w; }
;     __device__ __forceinline__ void operator()(const f32x4 (&acc)[2][2][4][2], const Unit& u, int wr, int wc, int fr, int fq) const {
;     ...
;             for (int m = 0; m < 4; ++m) { const int row = row0 + ai * HALF + m * 16;
;                 float s;
;                 if (nslot == 8) { const f32x4 a = *(const f32x4*)(ssq + (size_t)row * 8), b = *(const f32x4*)(ssq + (size_t)row * 8 + 4); s = ((a[0] + a[1]) + (a[2] + a[3])) + ((b[0] + b[1]) + (b[2] + b[3])); }
;                 else { const f32x4 a = *(const f32x4*)(ssq + (size_t)row * 4); s = (a[0] + a[1]) + (a[2] + a[3]); }
;                 const float rs = oscale / sqrtf(s * invK + EPS);
;                 f32x4 csA = {1.f, 0.f, 1.f, 0.f}, csB = {1.f, 0.f, 1.f, 0.f};
;                 if (dorope) { const int pos = row & (SEQ - 1); const float* cs = rope + ((size_t)pos * 32 + 16 * (wc & 1) + 4 * fq) * 2; csA = *(const f32x4*)cs; csB = *(const f32x4*)(cs + 4); }
; #pragma unroll
;                 for (int bj = 0; bj < 2; ++bj) { f32x4 v0 = acc[ai][bj][m][0] * rs, v1 = acc[ai][bj][m][1] * rs;
;                     if (dorope) rope8(v0, v1, csA, csB);
;                     *(u32x4*)(base + (size_t)row * ld + bj * HALF + cw) = pack8(v0, v1); } }
.LBB0_281:
	v_lshl_add_u32 v146, s4, 8, v1
	v_ashrrev_i32_e32 v147, 31, v146
	v_lshl_add_u64 v[156:157], v[146:147], 4, s[44:45]
	global_load_dwordx4 v[156:159], v[156:157], off
	s_lshl_b32 s48, s5, 8
	s_lshl_b64 s[28:29], s[48:49], 1
	s_add_u32 s4, s61, s28
	s_addc_u32 s17, s94, s29
	s_add_u32 s4, s4, 0xfffff000
	s_addc_u32 s17, s17, -1
	s_ashr_i32 s29, s48, 31
	s_mov_b32 s28, s48
	s_lshl_b64 s[28:29], s[28:29], 1
	s_add_u32 s28, s35, s28
	s_addc_u32 s29, s57, s29
	s_cmp_gt_i32 s5, 7
	s_cselect_b32 s5, s17, s29
	s_cselect_b32 s4, s4, s28
	v_lshl_add_u64 v[144:145], s[4:5], 0, v[138:139]
	s_waitcnt vmcnt(0)
	v_mov_b32_e32 v160, v157
	v_mov_b32_e32 v161, v158
	v_mov_b32_e32 v157, v159
	v_pk_add_f32 v[156:157], v[160:161], v[156:157]
	s_nop 0
	v_add_f32_e32 v155, v156, v157
	v_fmamk_f32 v155, v155, 0x3b800000, v153
	v_rsq_f32_e32 v156, v155
	s_nop 0
	v_lshlrev_b64 v[158:159], 12, v[146:147]
	v_pk_mul_f32 v[128:129], v[128:129], v[156:157] op_sel_hi:[1,0]
	v_pk_mul_f32 v[126:127], v[126:127], v[156:157] op_sel_hi:[1,0]
	v_pk_mul_f32 v[160:161], v[124:125], v[156:157] op_sel_hi:[1,0]
	v_pk_mul_f32 v[124:125], v[122:123], v[156:157] op_sel_hi:[1,0]
	v_lshl_add_u64 v[158:159], v[144:145], 0, v[158:159]
	v_cvt_pk_bf16_f32 v122, v126, v127
	v_cvt_pk_bf16_f32 v123, v128, v129
	v_cvt_pk_bf16_f32 v124, v124, v125
	v_cvt_pk_bf16_f32 v125, v160, v161
	v_pk_mul_f32 v[118:119], v[118:119], v[156:157] op_sel_hi:[1,0]
	global_store_dwordx4 v[158:159], v[122:125], off
	v_pk_mul_f32 v[120:121], v[120:121], v[156:157] op_sel_hi:[1,0]
	s_nop 0
	v_pk_mul_f32 v[122:123], v[116:117], v[156:157] op_sel_hi:[1,0]
	v_pk_mul_f32 v[116:117], v[114:115], v[156:157] op_sel_hi:[1,0]
	v_cvt_pk_bf16_f32 v114, v118, v119
	v_or_b32_e32 v118, 16, v146
	v_cvt_pk_bf16_f32 v115, v120, v121
	v_cvt_pk_bf16_f32 v116, v116, v117
	v_cvt_pk_bf16_f32 v117, v122, v123
	v_ashrrev_i32_e32 v119, 31, v118
	global_store_dwordx4 v[158:159], v[114:117], off offset:256
	s_nop 1
	v_lshl_add_u64 v[114:115], v[118:119], 4, s[44:45]
	global_load_dwordx4 v[114:117], v[114:115], off
	s_waitcnt vmcnt(0)
	v_mov_b32_e32 v120, v115
	v_mov_b32_e32 v121, v116
	v_mov_b32_e32 v115, v117
	v_pk_add_f32 v[114:115], v[120:121], v[114:115]
	s_nop 0
	v_add_f32_e32 v114, v114, v115
	v_fmamk_f32 v114, v114, 0x3b800000, v153
	v_rsq_f32_e32 v114, v114
	s_nop 0
	v_lshlrev_b64 v[116:117], 12, v[118:119]
	v_pk_mul_f32 v[112:113], v[112:113], v[114:115] op_sel_hi:[1,0]
	v_pk_mul_f32 v[110:111], v[110:111], v[114:115] op_sel_hi:[1,0]
	v_pk_mul_f32 v[118:119], v[108:109], v[114:115] op_sel_hi:[1,0]
	v_pk_mul_f32 v[108:109], v[106:107], v[114:115] op_sel_hi:[1,0]
	v_lshl_add_u64 v[116:117], v[144:145], 0, v[116:117]
	v_cvt_pk_bf16_f32 v106, v110, v111
	v_cvt_pk_bf16_f32 v107, v112, v113
	v_cvt_pk_bf16_f32 v108, v108, v109
	v_cvt_pk_bf16_f32 v109, v118, v119
	v_pk_mul_f32 v[102:103], v[102:103], v[114:115] op_sel_hi:[1,0]
	global_store_dwordx4 v[116:117], v[106:109], off
	v_pk_mul_f32 v[104:105], v[104:105], v[114:115] op_sel_hi:[1,0]
	s_nop 0
	v_pk_mul_f32 v[106:107], v[100:101], v[114:115] op_sel_hi:[1,0]
	v_pk_mul_f32 v[100:101], v[98:99], v[114:115] op_sel_hi:[1,0]
	v_cvt_pk_bf16_f32 v98, v102, v103
	v_or_b32_e32 v102, 32, v146
	v_cvt_pk_bf16_f32 v99, v104, v105
	v_cvt_pk_bf16_f32 v100, v100, v101
	v_cvt_pk_bf16_f32 v101, v106, v107
	v_ashrrev_i32_e32 v103, 31, v102
	global_store_dwordx4 v[116:117], v[98:101], off offset:256
	s_nop 1
	v_lshl_add_u64 v[98:99], v[102:103], 4, s[44:45]
	global_load_dwordx4 v[98:101], v[98:99], off
	s_waitcnt vmcnt(0)
	v_mov_b32_e32 v104, v99
	v_mov_b32_e32 v105, v100
	v_mov_b32_e32 v99, v101
	v_pk_add_f32 v[98:99], v[104:105], v[98:99]
	s_nop 0
	v_add_f32_e32 v98, v98, v99
	v_fmamk_f32 v98, v98, 0x3b800000, v153
	v_rsq_f32_e32 v98, v98
	s_nop 0
	v_lshlrev_b64 v[100:101], 12, v[102:103]
	v_pk_mul_f32 v[96:97], v[96:97], v[98:99] op_sel_hi:[1,0]
	v_pk_mul_f32 v[94:95], v[94:95], v[98:99] op_sel_hi:[1,0]
	v_pk_mul_f32 v[102:103], v[92:93], v[98:99] op_sel_hi:[1,0]
	v_pk_mul_f32 v[92:93], v[90:91], v[98:99] op_sel_hi:[1,0]
	v_lshl_add_u64 v[100:101], v[144:145], 0, v[100:101]
	v_cvt_pk_bf16_f32 v90, v94, v95
	v_cvt_pk_bf16_f32 v91, v96, v97
	v_cvt_pk_bf16_f32 v92, v92, v93
	v_cvt_pk_bf16_f32 v93, v102, v103
	v_pk_mul_f32 v[86:87], v[86:87], v[98:99] op_sel_hi:[1,0]
	global_store_dwordx4 v[100:101], v[90:93], off
	v_pk_mul_f32 v[88:89], v[88:89], v[98:99] op_sel_hi:[1,0]
	s_nop 0
	v_pk_mul_f32 v[90:91], v[84:85], v[98:99] op_sel_hi:[1,0]
	v_pk_mul_f32 v[84:85], v[82:83], v[98:99] op_sel_hi:[1,0]
	v_cvt_pk_bf16_f32 v82, v86, v87
	v_or_b32_e32 v86, 48, v146
	v_cvt_pk_bf16_f32 v83, v88, v89
	v_cvt_pk_bf16_f32 v84, v84, v85
	v_cvt_pk_bf16_f32 v85, v90, v91
	v_ashrrev_i32_e32 v87, 31, v86
	global_store_dwordx4 v[100:101], v[82:85], off offset:256
	s_nop 1
	v_lshl_add_u64 v[82:83], v[86:87], 4, s[44:45]
	global_load_dwordx4 v[82:85], v[82:83], off
	s_waitcnt vmcnt(0)
	v_mov_b32_e32 v88, v83
	v_mov_b32_e32 v89, v84
	v_mov_b32_e32 v83, v85
	v_pk_add_f32 v[82:83], v[88:89], v[82:83]
	s_nop 0
	v_add_f32_e32 v82, v82, v83
	v_fmamk_f32 v82, v82, 0x3b800000, v153
	v_rsq_f32_e32 v82, v82
	s_nop 0
	v_lshlrev_b64 v[84:85], 12, v[86:87]
	v_pk_mul_f32 v[80:81], v[80:81], v[82:83] op_sel_hi:[1,0]
	v_pk_mul_f32 v[78:79], v[78:79], v[82:83] op_sel_hi:[1,0]
	v_pk_mul_f32 v[86:87], v[76:77], v[82:83] op_sel_hi:[1,0]
	v_pk_mul_f32 v[76:77], v[74:75], v[82:83] op_sel_hi:[1,0]
	v_lshl_add_u64 v[84:85], v[144:145], 0, v[84:85]
	v_cvt_pk_bf16_f32 v74, v78, v79
	v_cvt_pk_bf16_f32 v75, v80, v81
	v_cvt_pk_bf16_f32 v76, v76, v77
	v_cvt_pk_bf16_f32 v77, v86, v87
	v_pk_mul_f32 v[70:71], v[70:71], v[82:83] op_sel_hi:[1,0]
	global_store_dwordx4 v[84:85], v[74:77], off
	v_pk_mul_f32 v[72:73], v[72:73], v[82:83] op_sel_hi:[1,0]
	s_nop 0
	v_pk_mul_f32 v[74:75], v[68:69], v[82:83] op_sel_hi:[1,0]
	v_pk_mul_f32 v[68:69], v[66:67], v[82:83] op_sel_hi:[1,0]
	v_cvt_pk_bf16_f32 v66, v70, v71
	v_add_u32_e32 v70, 0x80, v146
	v_cvt_pk_bf16_f32 v67, v72, v73
	v_cvt_pk_bf16_f32 v68, v68, v69
	v_cvt_pk_bf16_f32 v69, v74, v75
	v_ashrrev_i32_e32 v71, 31, v70
	global_store_dwordx4 v[84:85], v[66:69], off offset:256
	s_nop 1
	v_lshl_add_u64 v[66:67], v[70:71], 4, s[44:45]
	global_load_dwordx4 v[66:69], v[66:67], off
	s_waitcnt vmcnt(0)
; __device__ __forceinline__ u32x4 pack8(const f32x4 a, const f32x4 b) { u32x4 w; w.x = cvt_pk_bf16(a[0], a[1]); w.y = cvt_pk_bf16(a[2], a[3]); w.z = cvt_pk_bf16(b[0], b[1]); w.w = cvt_pk_bf16(b[2], b[3]); return w; }
;     __device__ __forceinline__ void operator()(const f32x4 (&acc)[2][2][4][2], const Unit& u, int wr, int wc, int fr, int fq) const {
;     ...
;             for (int m = 0; m < 4; ++m) { const int row = row0 + ai * HALF + m * 16;
;                 float s;
;                 if (nslot == 8) { const f32x4 a = *(const f32x4*)(ssq + (size_t)row * 8), b = *(const f32x4*)(ssq + (size_t)row * 8 + 4); s = ((a[0] + a[1]) + (a[2] + a[3])) + ((b[0] + b[1]) + (b[2] + b[3])); }
;                 else { const f32x4 a = *(const f32x4*)(ssq + (size_t)row * 4); s = (a[0] + a[1]) + (a[2] + a[3]); }
;                 const float rs = oscale / sqrtf(s * invK + EPS);
;                 f32x4 csA = {1.f, 0.f, 1.f, 0.f}, csB = {1.f, 0.f, 1.f, 0.f};
;                 if (dorope) { const int pos = row & (SEQ - 1); const float* cs = rope + ((size_t)pos * 32 + 16 * (wc & 1) + 4 * fq) * 2; csA = *(const f32x4*)cs; csB = *(const f32x4*)(cs + 4); }
; #pragma unroll
;                 for (int bj = 0; bj < 2; ++bj) { f32x4 v0 = acc[ai][bj][m][0] * rs, v1 = acc[ai][bj][m][1] * rs;
;                     if (dorope) rope8(v0, v1, csA, csB);
;                     *(u32x4*)(base + (size_t)row * ld + bj * HALF + cw) = pack8(v0, v1); } }
	v_mov_b32_e32 v72, v67
	v_mov_b32_e32 v73, v68
	v_mov_b32_e32 v67, v69
	v_pk_add_f32 v[66:67], v[72:73], v[66:67]
	s_nop 0
	v_add_f32_e32 v66, v66, v67
	v_fmamk_f32 v66, v66, 0x3b800000, v153
	v_rsq_f32_e32 v66, v66
	s_nop 0
	v_lshlrev_b64 v[68:69], 12, v[70:71]
	v_pk_mul_f32 v[64:65], v[64:65], v[66:67] op_sel_hi:[1,0]
	v_pk_mul_f32 v[62:63], v[62:63], v[66:67] op_sel_hi:[1,0]
	v_pk_mul_f32 v[70:71], v[60:61], v[66:67] op_sel_hi:[1,0]
	v_pk_mul_f32 v[60:61], v[58:59], v[66:67] op_sel_hi:[1,0]
	v_lshl_add_u64 v[68:69], v[144:145], 0, v[68:69]
	v_cvt_pk_bf16_f32 v58, v62, v63
	v_cvt_pk_bf16_f32 v59, v64, v65
	v_cvt_pk_bf16_f32 v60, v60, v61
	v_cvt_pk_bf16_f32 v61, v70, v71
	v_pk_mul_f32 v[54:55], v[54:55], v[66:67] op_sel_hi:[1,0]
	global_store_dwordx4 v[68:69], v[58:61], off
	v_pk_mul_f32 v[56:57], v[56:57], v[66:67] op_sel_hi:[1,0]
	s_nop 0
	v_pk_mul_f32 v[58:59], v[52:53], v[66:67] op_sel_hi:[1,0]
	v_pk_mul_f32 v[52:53], v[50:51], v[66:67] op_sel_hi:[1,0]
	v_cvt_pk_bf16_f32 v50, v54, v55
	v_add_u32_e32 v54, 0x90, v146
	v_cvt_pk_bf16_f32 v51, v56, v57
	v_cvt_pk_bf16_f32 v52, v52, v53
	v_cvt_pk_bf16_f32 v53, v58, v59
	v_ashrrev_i32_e32 v55, 31, v54
	global_store_dwordx4 v[68:69], v[50:53], off offset:256
	s_nop 1
	v_lshl_add_u64 v[50:51], v[54:55], 4, s[44:45]
	global_load_dwordx4 v[50:53], v[50:51], off
	s_waitcnt vmcnt(0)
	v_mov_b32_e32 v56, v51
	v_mov_b32_e32 v57, v52
	v_mov_b32_e32 v51, v53
	v_pk_add_f32 v[50:51], v[56:57], v[50:51]
	s_nop 0
	v_add_f32_e32 v50, v50, v51
	v_fmamk_f32 v50, v50, 0x3b800000, v153
	v_rsq_f32_e32 v50, v50
	s_nop 0
	v_lshlrev_b64 v[52:53], 12, v[54:55]
	v_pk_mul_f32 v[48:49], v[48:49], v[50:51] op_sel_hi:[1,0]
	v_pk_mul_f32 v[46:47], v[46:47], v[50:51] op_sel_hi:[1,0]
	v_pk_mul_f32 v[54:55], v[44:45], v[50:51] op_sel_hi:[1,0]
	v_pk_mul_f32 v[44:45], v[42:43], v[50:51] op_sel_hi:[1,0]
	v_lshl_add_u64 v[52:53], v[144:145], 0, v[52:53]
	v_cvt_pk_bf16_f32 v42, v46, v47
	v_cvt_pk_bf16_f32 v43, v48, v49
	v_cvt_pk_bf16_f32 v44, v44, v45
	v_cvt_pk_bf16_f32 v45, v54, v55
	v_pk_mul_f32 v[38:39], v[38:39], v[50:51] op_sel_hi:[1,0]
	global_store_dwordx4 v[52:53], v[42:45], off
	v_pk_mul_f32 v[40:41], v[40:41], v[50:51] op_sel_hi:[1,0]
	s_nop 0
	v_pk_mul_f32 v[42:43], v[36:37], v[50:51] op_sel_hi:[1,0]
	v_pk_mul_f32 v[36:37], v[34:35], v[50:51] op_sel_hi:[1,0]
	v_cvt_pk_bf16_f32 v34, v38, v39
	v_add_u32_e32 v38, 0xa0, v146
	v_cvt_pk_bf16_f32 v35, v40, v41
	v_cvt_pk_bf16_f32 v36, v36, v37
	v_cvt_pk_bf16_f32 v37, v42, v43
	v_ashrrev_i32_e32 v39, 31, v38
	global_store_dwordx4 v[52:53], v[34:37], off offset:256
	s_nop 1
	v_lshl_add_u64 v[34:35], v[38:39], 4, s[44:45]
	global_load_dwordx4 v[34:37], v[34:35], off
	s_waitcnt vmcnt(0)
	v_mov_b32_e32 v40, v35
	v_mov_b32_e32 v41, v36
	v_mov_b32_e32 v35, v37
	v_pk_add_f32 v[34:35], v[40:41], v[34:35]
	s_nop 0
	v_add_f32_e32 v34, v34, v35
	v_fmamk_f32 v34, v34, 0x3b800000, v153
	v_rsq_f32_e32 v34, v34
	s_nop 0
	v_lshlrev_b64 v[36:37], 12, v[38:39]
	v_pk_mul_f32 v[32:33], v[32:33], v[34:35] op_sel_hi:[1,0]
	v_pk_mul_f32 v[30:31], v[30:31], v[34:35] op_sel_hi:[1,0]
	v_pk_mul_f32 v[38:39], v[28:29], v[34:35] op_sel_hi:[1,0]
	v_pk_mul_f32 v[28:29], v[26:27], v[34:35] op_sel_hi:[1,0]
	v_lshl_add_u64 v[36:37], v[144:145], 0, v[36:37]
	v_cvt_pk_bf16_f32 v26, v30, v31
	v_cvt_pk_bf16_f32 v27, v32, v33
	v_cvt_pk_bf16_f32 v28, v28, v29
	v_cvt_pk_bf16_f32 v29, v38, v39
	v_pk_mul_f32 v[22:23], v[22:23], v[34:35] op_sel_hi:[1,0]
	global_store_dwordx4 v[36:37], v[26:29], off
	v_pk_mul_f32 v[24:25], v[24:25], v[34:35] op_sel_hi:[1,0]
	s_nop 0
	v_pk_mul_f32 v[26:27], v[20:21], v[34:35] op_sel_hi:[1,0]
	v_pk_mul_f32 v[20:21], v[18:19], v[34:35] op_sel_hi:[1,0]
	v_cvt_pk_bf16_f32 v18, v22, v23
	v_add_u32_e32 v22, 0xb0, v146
	v_cvt_pk_bf16_f32 v19, v24, v25
	v_cvt_pk_bf16_f32 v20, v20, v21
	v_cvt_pk_bf16_f32 v21, v26, v27
	v_ashrrev_i32_e32 v23, 31, v22
	global_store_dwordx4 v[36:37], v[18:21], off offset:256
	s_nop 1
	v_lshl_add_u64 v[18:19], v[22:23], 4, s[44:45]
	global_load_dwordx4 v[18:21], v[18:19], off
	s_waitcnt vmcnt(0)
	v_mov_b32_e32 v24, v19
	v_mov_b32_e32 v25, v20
	v_mov_b32_e32 v19, v21
	v_pk_add_f32 v[18:19], v[24:25], v[18:19]
	s_nop 0
	v_add_f32_e32 v18, v18, v19
	v_fmamk_f32 v18, v18, 0x3b800000, v153
	v_rsq_f32_e32 v18, v18
	s_nop 0
	s_mov_b64 s[4:5], -1
	v_lshlrev_b64 v[20:21], 12, v[22:23]
	v_pk_mul_f32 v[16:17], v[16:17], v[18:19] op_sel_hi:[1,0]
	v_pk_mul_f32 v[14:15], v[14:15], v[18:19] op_sel_hi:[1,0]
	v_pk_mul_f32 v[22:23], v[12:13], v[18:19] op_sel_hi:[1,0]
	v_pk_mul_f32 v[12:13], v[10:11], v[18:19] op_sel_hi:[1,0]
	v_lshl_add_u64 v[20:21], v[144:145], 0, v[20:21]
	v_cvt_pk_bf16_f32 v10, v14, v15
	v_cvt_pk_bf16_f32 v11, v16, v17
	v_cvt_pk_bf16_f32 v12, v12, v13
	v_cvt_pk_bf16_f32 v13, v22, v23
	global_store_dwordx4 v[20:21], v[10:13], off
	v_pk_mul_f32 v[8:9], v[8:9], v[18:19] op_sel_hi:[1,0]
	v_pk_mul_f32 v[6:7], v[6:7], v[18:19] op_sel_hi:[1,0]
	v_pk_mul_f32 v[10:11], v[4:5], v[18:19] op_sel_hi:[1,0]
	v_pk_mul_f32 v[4:5], v[2:3], v[18:19] op_sel_hi:[1,0]
	v_cvt_pk_bf16_f32 v2, v6, v7
	v_cvt_pk_bf16_f32 v3, v8, v9
	v_cvt_pk_bf16_f32 v4, v4, v5
	v_cvt_pk_bf16_f32 v5, v10, v11
	s_andn2_b64 vcc, exec, s[0:1]
	global_store_dwordx4 v[20:21], v[2:5], off offset:256
	s_cbranch_vccnz .LBB0_270
	s_andn2_b64 vcc, exec, s[50:51]
	s_cbranch_vccnz .LBB0_269
	s_barrier
	s_branch .LBB0_269

; __device__ __forceinline__ u32x4 pack8(const f32x4 a, const f32x4 b) { u32x4 w; w.x = cvt_pk_bf16(a[0], a[1]); w.y = cvt_pk_bf16(a[2], a[3]); w.z = cvt_pk_bf16(b[0], b[1]); w.w = cvt_pk_bf16(b[2], b[3]); return w; }
;     __device__ __forceinline__ void operator()(const f32x4 (&acc)[2][2][4][2], const Unit& u, int wr, int wc, int fr, int fq) const {
;     ...
;                 for (int n = 0; n < 2; ++n) { f32x4 r1, r2;
; #pragma unroll
;                     for (int e = 0; e < 4; ++e) { const float a0 = acc[ai][0][m][n][e]; r1[e] = __shfl(a0, src1); r2[e] = __shfl(a0, src2); }
;                     f32x4 a1, a2;
; #pragma unroll
;                     for (int e = 0; e < 4; ++e) { a1[e] = fr >= 1 ? r1[e] : p1[n][e]; a2[e] = fr >= 2 ? r2[e] : p2[n][e]; }
;                     p1[n] = r1; p2[n] = r2;
;                     const f32x4 c = bb[n] + w0[n] * a2 + w1[n] * a1 + w2[n] * acc[ai][0][m][n];
; #pragma unroll
;                     for (int e = 0; e < 4; ++e) { const float x = c[e]; const float uu = 0.7978845608028654f * (x + 0.044715f * x * x * x);
;                         const float gl = x * __builtin_amdgcn_rcpf(1.f + __builtin_amdgcn_exp2f(-2.885390081777927f * uu)); o[n][e] = gl * acc[ai][1][m][n][e]; } }
;                 const int row = u.pm * BM + ai * HALF + wr * 64 + m * 16 + fr;
;                 if (!(m == 0 && fr < 2)) *(u32x4*)(G + (size_t)row * DFF + f0) = pack8(o[0], o[1]);
;                 if (m == 0 && fr < 2) { float* ah = AH + ((size_t)jb * 4 + 2 + fr) * DFF + f0; *(f32x4*)ah = acc[ai][0][0][0]; *(f32x4*)(ah + 4) = acc[ai][0][0][1];
;                     float* bh = BH + ((size_t)jb * 2 + fr) * DFF + f0; *(f32x4*)bh = acc[ai][1][0][0]; *(f32x4*)(bh + 4) = acc[ai][1][0][1]; }
;                 if (m == 3 && fr >= 14) { float* ah = AH + ((size_t)jb * 4 + (fr - 14)) * DFF + f0; *(f32x4*)ah = acc[ai][0][3][0]; *(f32x4*)(ah + 4) = acc[ai][0][3][1]; }
.LBB0_911:
	v_lshl_or_b32 v186, s67, 7, v175
	v_ashrrev_i32_e32 v187, 31, v186
	v_lshlrev_b64 v[188:189], 2, v[186:187]
	v_lshl_add_u64 v[86:87], s[24:25], 0, v[188:189]
	v_lshl_add_u64 v[90:91], s[40:41], 0, v[188:189]
	v_lshl_add_u64 v[94:95], s[44:45], 0, v[188:189]
	v_lshl_add_u64 v[110:111], s[26:27], 0, v[188:189]
	global_load_dwordx4 v[82:85], v[86:87], off offset:16
	global_load_dwordx4 v[98:101], v[86:87], off
	s_nop 0
	global_load_dwordx4 v[86:89], v[90:91], off offset:16
	global_load_dwordx4 v[102:105], v[90:91], off
	s_nop 0
	global_load_dwordx4 v[90:93], v[94:95], off offset:16
	global_load_dwordx4 v[106:109], v[94:95], off
	s_nop 0
	global_load_dwordx4 v[94:97], v[110:111], off offset:16
	s_nop 0
	global_load_dwordx4 v[110:113], v[110:111], off
	ds_bpermute_b32 v200, v212, v158
	ds_bpermute_b32 v198, v213, v158
	ds_bpermute_b32 v201, v212, v159
	ds_bpermute_b32 v199, v213, v159
	ds_bpermute_b32 v196, v212, v160
	ds_bpermute_b32 v194, v213, v160
	ds_bpermute_b32 v197, v212, v161
	ds_bpermute_b32 v195, v213, v161
	ds_bpermute_b32 v192, v212, v154
	ds_bpermute_b32 v190, v213, v154
	ds_bpermute_b32 v193, v212, v155
	ds_bpermute_b32 v191, v213, v155
	ds_bpermute_b32 v204, v212, v156
	ds_bpermute_b32 v202, v213, v156
	ds_bpermute_b32 v205, v212, v157
	ds_bpermute_b32 v203, v213, v157
	v_lshl_add_u32 v215, s66, 8, v165
	s_and_saveexec_b64 s[68:69], s[8:9]
	s_xor_b64 s[68:69], exec, s[68:69]
	s_cbranch_execz .LBB0_913
	s_waitcnt vmcnt(0) lgkmcnt(0)
	v_pk_fma_f32 v[216:217], v[84:85], v[202:203], v[96:97]
	s_nop 0
	v_pk_fma_f32 v[216:217], v[88:89], v[204:205], v[216:217]
	s_nop 0
	v_pk_fma_f32 v[216:217], v[156:157], v[92:93], v[216:217]
	s_nop 0
	v_mul_f32_e32 v218, 0x3d372713, v217
	v_mul_f32_e32 v218, v217, v218
	v_mul_f32_e32 v219, 0x3d372713, v216
	v_fma_f32 v218, v217, v218, v217
	v_mul_f32_e32 v219, v216, v219
	v_fma_f32 v219, v216, v219, v216
	v_mul_f32_e32 v218, 0xc0135761, v218
	v_exp_f32_e32 v218, v218
	v_mul_f32_e32 v219, 0xc0135761, v219
	v_exp_f32_e32 v220, v219
	v_add_f32_e32 v218, 1.0, v218
	v_rcp_f32_e32 v219, v218
	v_add_f32_e32 v218, 1.0, v220
	v_rcp_f32_e32 v218, v218
	s_nop 0
	v_pk_mul_f32 v[216:217], v[216:217], v[218:219]
	v_pk_fma_f32 v[218:219], v[98:99], v[198:199], v[110:111]
	s_nop 0
	v_pk_fma_f32 v[218:219], v[102:103], v[200:201], v[218:219]
	s_nop 0
	v_pk_fma_f32 v[218:219], v[158:159], v[106:107], v[218:219]
	s_nop 0
	v_mul_f32_e32 v220, 0x3d372713, v218
	v_mul_f32_e32 v220, v218, v220
	v_fma_f32 v220, v218, v220, v218
	v_mul_f32_e32 v220, 0xc0135761, v220
	v_exp_f32_e32 v222, v220
	v_mul_f32_e32 v220, 0x3d372713, v219
	v_mul_f32_e32 v220, v219, v220
	v_fma_f32 v220, v219, v220, v219
	v_mul_f32_e32 v220, 0xc0135761, v220
	v_exp_f32_e32 v223, v220
	v_pk_mul_f32 v[220:221], v[148:149], v[216:217]
	v_add_f32_e32 v216, 1.0, v222
	v_rcp_f32_e32 v216, v216
	v_add_f32_e32 v217, 1.0, v223
	v_pk_fma_f32 v[222:223], v[100:101], v[194:195], v[112:113]
	v_rcp_f32_e32 v217, v217
	v_pk_fma_f32 v[222:223], v[104:105], v[196:197], v[222:223]
	v_pk_mul_f32 v[216:217], v[218:219], v[216:217]
	v_pk_fma_f32 v[222:223], v[160:161], v[108:109], v[222:223]
	v_pk_mul_f32 v[216:217], v[150:151], v[216:217]
	v_mul_f32_e32 v224, 0x3d372713, v222
	v_mul_f32_e32 v225, 0x3d372713, v223
	v_mul_f32_e32 v224, v222, v224
	v_mul_f32_e32 v225, v223, v225
	v_fma_f32 v224, v222, v224, v222
	v_fma_f32 v225, v223, v225, v223
	v_mul_f32_e32 v224, 0xc0135761, v224
	v_mul_f32_e32 v225, 0xc0135761, v225
	v_exp_f32_e32 v224, v224
	v_exp_f32_e32 v225, v225
	v_cvt_pk_bf16_f32 v216, v216, v217
	v_add_f32_e32 v218, 1.0, v224
	v_add_f32_e32 v219, 1.0, v225
	v_pk_fma_f32 v[224:225], v[82:83], v[190:191], v[94:95]
	v_rcp_f32_e32 v218, v218
	v_pk_fma_f32 v[224:225], v[86:87], v[192:193], v[224:225]
	v_rcp_f32_e32 v219, v219
	v_pk_fma_f32 v[224:225], v[154:155], v[90:91], v[224:225]
	v_pk_mul_f32 v[218:219], v[222:223], v[218:219]
	v_mul_f32_e32 v226, 0x3d372713, v225
	v_mul_f32_e32 v226, v225, v226
	v_mul_f32_e32 v227, 0x3d372713, v224
	v_fma_f32 v226, v225, v226, v225
	v_mul_f32_e32 v227, v224, v227
	v_fma_f32 v227, v224, v227, v224
	v_mul_f32_e32 v226, 0xc0135761, v226
	v_exp_f32_e32 v226, v226
	v_mul_f32_e32 v227, 0xc0135761, v227
	v_exp_f32_e32 v228, v227
	v_pk_mul_f32 v[218:219], v[152:153], v[218:219]
	v_add_f32_e32 v226, 1.0, v226
	v_rcp_f32_e32 v227, v226
	v_add_f32_e32 v226, 1.0, v228
	v_rcp_f32_e32 v226, v226
	v_cvt_pk_bf16_f32 v217, v218, v219
	v_cvt_pk_bf16_f32 v219, v220, v221
	v_mov_b64_e32 v[220:221], s[10:11]
	v_pk_mul_f32 v[222:223], v[224:225], v[226:227]
	v_mad_i64_i32 v[220:221], s[70:71], v215, s79, v[220:221]
	v_pk_mul_f32 v[222:223], v[146:147], v[222:223]
	v_lshl_add_u64 v[220:221], v[186:187], 1, v[220:221]
	v_cvt_pk_bf16_f32 v218, v222, v223
	global_store_dwordx4 v[220:221], v[216:219], off

; __device__ __forceinline__ u32x4 pack8(const f32x4 a, const f32x4 b) { u32x4 w; w.x = cvt_pk_bf16(a[0], a[1]); w.y = cvt_pk_bf16(a[2], a[3]); w.z = cvt_pk_bf16(b[0], b[1]); w.w = cvt_pk_bf16(b[2], b[3]); return w; }
;     __device__ __forceinline__ void operator()(const f32x4 (&acc)[2][2][4][2], const Unit& u, int wr, int wc, int fr, int fq) const {
;     ...
;                 for (int n = 0; n < 2; ++n) { f32x4 r1, r2;
; #pragma unroll
;                     for (int e = 0; e < 4; ++e) { const float a0 = acc[ai][0][m][n][e]; r1[e] = __shfl(a0, src1); r2[e] = __shfl(a0, src2); }
;                     f32x4 a1, a2;
; #pragma unroll
;                     for (int e = 0; e < 4; ++e) { a1[e] = fr >= 1 ? r1[e] : p1[n][e]; a2[e] = fr >= 2 ? r2[e] : p2[n][e]; }
;                     p1[n] = r1; p2[n] = r2;
;                     const f32x4 c = bb[n] + w0[n] * a2 + w1[n] * a1 + w2[n] * acc[ai][0][m][n];
; #pragma unroll
;                     for (int e = 0; e < 4; ++e) { const float x = c[e]; const float uu = 0.7978845608028654f * (x + 0.044715f * x * x * x);
;                         const float gl = x * __builtin_amdgcn_rcpf(1.f + __builtin_amdgcn_exp2f(-2.885390081777927f * uu)); o[n][e] = gl * acc[ai][1][m][n][e]; } }
;                 const int row = u.pm * BM + ai * HALF + wr * 64 + m * 16 + fr;
;                 if (!(m == 0 && fr < 2)) *(u32x4*)(G + (size_t)row * DFF + f0) = pack8(o[0], o[1]);
;                 if (m == 0 && fr < 2) { float* ah = AH + ((size_t)jb * 4 + 2 + fr) * DFF + f0; *(f32x4*)ah = acc[ai][0][0][0]; *(f32x4*)(ah + 4) = acc[ai][0][0][1];
;                     float* bh = BH + ((size_t)jb * 2 + fr) * DFF + f0; *(f32x4*)bh = acc[ai][1][0][0]; *(f32x4*)(bh + 4) = acc[ai][1][0][1]; }
;                 if (m == 3 && fr >= 14) { float* ah = AH + ((size_t)jb * 4 + (fr - 14)) * DFF + f0; *(f32x4*)ah = acc[ai][0][3][0]; *(f32x4*)(ah + 4) = acc[ai][0][3][1]; }
.LBB0_915:
	s_or_b64 exec, exec, s[70:71]
	ds_bpermute_b32 v159, v213, v141
	ds_bpermute_b32 v160, v213, v140
	ds_bpermute_b32 v157, v212, v141
	ds_bpermute_b32 v158, v212, v140
	ds_bpermute_b32 v151, v213, v142
	s_waitcnt lgkmcnt(0)
	v_cndmask_b32_e64 v149, v203, v159, s[8:9]
	v_cndmask_b32_e64 v148, v202, v160, s[8:9]
	v_cndmask_b32_e64 v147, v157, v205, s[0:1]
	v_cndmask_b32_e64 v146, v158, v204, s[0:1]
	s_waitcnt vmcnt(0)
	v_pk_fma_f32 v[148:149], v[84:85], v[148:149], v[96:97]
	ds_bpermute_b32 v153, v213, v143
	v_pk_fma_f32 v[146:147], v[88:89], v[146:147], v[148:149]
	ds_bpermute_b32 v150, v212, v142
	v_pk_fma_f32 v[140:141], v[140:141], v[92:93], v[146:147]
	ds_bpermute_b32 v152, v212, v143
	v_mul_f32_e32 v146, 0x3d372713, v141
	v_mul_f32_e32 v146, v141, v146
	v_mul_f32_e32 v147, 0x3d372713, v140
	v_fma_f32 v146, v141, v146, v141
	v_mul_f32_e32 v147, v140, v147
	v_fma_f32 v147, v140, v147, v140
	v_mul_f32_e32 v146, 0xc0135761, v146
	v_exp_f32_e32 v146, v146
	v_mul_f32_e32 v147, 0xc0135761, v147
	v_exp_f32_e32 v148, v147
	s_waitcnt lgkmcnt(2)
	v_cndmask_b32_e64 v149, v199, v153, s[8:9]
	v_add_f32_e32 v146, 1.0, v146
	v_rcp_f32_e32 v147, v146
	v_add_f32_e32 v146, 1.0, v148
	v_rcp_f32_e32 v146, v146
	v_cndmask_b32_e64 v148, v198, v151, s[8:9]
	v_pk_fma_f32 v[148:149], v[98:99], v[148:149], v[110:111]
	ds_bpermute_b32 v155, v213, v144
	v_pk_mul_f32 v[140:141], v[140:141], v[146:147]
	s_waitcnt lgkmcnt(1)
	v_cndmask_b32_e64 v147, v152, v201, s[0:1]
	v_cndmask_b32_e64 v146, v150, v200, s[0:1]
	v_pk_fma_f32 v[146:147], v[102:103], v[146:147], v[148:149]
	ds_bpermute_b32 v161, v213, v145
	v_pk_fma_f32 v[142:143], v[142:143], v[106:107], v[146:147]
	ds_bpermute_b32 v154, v212, v144
	v_mul_f32_e32 v146, 0x3d372713, v142
	v_mul_f32_e32 v147, 0x3d372713, v143
	v_mul_f32_e32 v146, v142, v146
	v_mul_f32_e32 v147, v143, v147
	v_fma_f32 v146, v142, v146, v142
	v_fma_f32 v147, v143, v147, v143
	ds_bpermute_b32 v156, v212, v145
	v_mul_f32_e32 v146, 0xc0135761, v146
	v_mul_f32_e32 v147, 0xc0135761, v147
	v_exp_f32_e32 v146, v146
	v_exp_f32_e32 v147, v147
	s_waitcnt lgkmcnt(2)
	v_cndmask_b32_e64 v149, v195, v161, s[8:9]
	v_cndmask_b32_e64 v148, v194, v155, s[8:9]
	v_pk_mul_f32 v[132:133], v[132:133], v[140:141]
	v_add_f32_e32 v140, 1.0, v146
	v_add_f32_e32 v141, 1.0, v147
	s_waitcnt lgkmcnt(0)
	v_cndmask_b32_e64 v147, v156, v197, s[0:1]
	v_cndmask_b32_e64 v146, v154, v196, s[0:1]
	v_pk_fma_f32 v[148:149], v[100:101], v[148:149], v[112:113]
	ds_bpermute_b32 v203, v213, v138
	v_pk_fma_f32 v[146:147], v[104:105], v[146:147], v[148:149]
	ds_bpermute_b32 v205, v213, v139
	v_pk_fma_f32 v[144:145], v[144:145], v[108:109], v[146:147]
	ds_bpermute_b32 v202, v212, v138
	v_mul_f32_e32 v146, 0x3d372713, v144
	v_mul_f32_e32 v147, 0x3d372713, v145
	v_mul_f32_e32 v146, v144, v146
	v_mul_f32_e32 v147, v145, v147
	v_fma_f32 v146, v144, v146, v144
	v_fma_f32 v147, v145, v147, v145
	ds_bpermute_b32 v204, v212, v139
	v_mul_f32_e32 v146, 0xc0135761, v146
	v_mul_f32_e32 v147, 0xc0135761, v147
	v_rcp_f32_e32 v140, v140
	v_rcp_f32_e32 v141, v141
	v_exp_f32_e32 v146, v146
	v_exp_f32_e32 v147, v147
	s_waitcnt lgkmcnt(2)
	v_cndmask_b32_e64 v149, v191, v205, s[8:9]
	v_cndmask_b32_e64 v148, v190, v203, s[8:9]
	v_pk_mul_f32 v[140:141], v[142:143], v[140:141]
	v_add_f32_e32 v142, 1.0, v146
	v_add_f32_e32 v143, 1.0, v147
	s_waitcnt lgkmcnt(0)
	v_cndmask_b32_e64 v147, v204, v193, s[0:1]
	v_cndmask_b32_e64 v146, v202, v192, s[0:1]
	v_pk_fma_f32 v[148:149], v[82:83], v[148:149], v[94:95]
	v_rcp_f32_e32 v142, v142
	v_pk_fma_f32 v[146:147], v[86:87], v[146:147], v[148:149]
	v_rcp_f32_e32 v143, v143
	v_pk_fma_f32 v[138:139], v[138:139], v[90:91], v[146:147]
	v_pk_mul_f32 v[134:135], v[134:135], v[140:141]
	v_mul_f32_e32 v146, 0x3d372713, v139
	v_mul_f32_e32 v146, v139, v146
	v_mul_f32_e32 v147, 0x3d372713, v138
	v_fma_f32 v146, v139, v146, v139
	v_mul_f32_e32 v147, v138, v147
	v_fma_f32 v147, v138, v147, v138
	v_mul_f32_e32 v146, 0xc0135761, v146
	v_exp_f32_e32 v146, v146
	v_mul_f32_e32 v147, 0xc0135761, v147
	v_exp_f32_e32 v148, v147
	v_pk_mul_f32 v[140:141], v[144:145], v[142:143]
	v_add_f32_e32 v146, 1.0, v146
	v_rcp_f32_e32 v147, v146
	v_add_f32_e32 v146, 1.0, v148
	v_rcp_f32_e32 v146, v146
	ds_bpermute_b32 v148, v213, v124
	v_pk_mul_f32 v[136:137], v[136:137], v[140:141]
	ds_bpermute_b32 v145, v212, v125
	v_pk_mul_f32 v[138:139], v[138:139], v[146:147]
	ds_bpermute_b32 v147, v213, v125
	ds_bpermute_b32 v146, v212, v124
	v_pk_mul_f32 v[130:131], v[130:131], v[138:139]
	v_or_b32_e32 v138, 16, v215
	v_cvt_pk_bf16_f32 v134, v134, v135
	v_cvt_pk_bf16_f32 v135, v136, v137
	v_cvt_pk_bf16_f32 v137, v132, v133
	v_mov_b64_e32 v[132:133], s[10:11]
	v_cvt_pk_bf16_f32 v136, v130, v131
	v_mad_i64_i32 v[138:139], s[70:71], v138, s79, v[132:133]
	v_lshlrev_b64 v[130:131], 1, v[186:187]
	v_lshl_add_u64 v[138:139], v[138:139], 0, v[130:131]
	global_store_dwordx4 v[138:139], v[134:137], off
	ds_bpermute_b32 v139, v213, v126
	ds_bpermute_b32 v141, v213, v127
	s_waitcnt lgkmcnt(3)
	v_cndmask_b32_e64 v137, v159, v147, s[8:9]
	v_cndmask_b32_e64 v136, v160, v148, s[8:9]
	v_cndmask_b32_e64 v135, v145, v157, s[0:1]
	s_waitcnt lgkmcnt(2)
	v_cndmask_b32_e64 v134, v146, v158, s[0:1]
	v_pk_fma_f32 v[136:137], v[84:85], v[136:137], v[96:97]
	ds_bpermute_b32 v138, v212, v126
	v_pk_fma_f32 v[134:135], v[88:89], v[134:135], v[136:137]
	ds_bpermute_b32 v140, v212, v127
	v_pk_fma_f32 v[124:125], v[124:125], v[92:93], v[134:135]
	s_waitcnt lgkmcnt(2)
; __device__ __forceinline__ u32x4 pack8(const f32x4 a, const f32x4 b) { u32x4 w; w.x = cvt_pk_bf16(a[0], a[1]); w.y = cvt_pk_bf16(a[2], a[3]); w.z = cvt_pk_bf16(b[0], b[1]); w.w = cvt_pk_bf16(b[2], b[3]); return w; }
;     __device__ __forceinline__ void operator()(const f32x4 (&acc)[2][2][4][2], const Unit& u, int wr, int wc, int fr, int fq) const {
;     ...
;                 for (int n = 0; n < 2; ++n) { f32x4 r1, r2;
; #pragma unroll
;                     for (int e = 0; e < 4; ++e) { const float a0 = acc[ai][0][m][n][e]; r1[e] = __shfl(a0, src1); r2[e] = __shfl(a0, src2); }
;                     f32x4 a1, a2;
; #pragma unroll
;                     for (int e = 0; e < 4; ++e) { a1[e] = fr >= 1 ? r1[e] : p1[n][e]; a2[e] = fr >= 2 ? r2[e] : p2[n][e]; }
;                     p1[n] = r1; p2[n] = r2;
;                     const f32x4 c = bb[n] + w0[n] * a2 + w1[n] * a1 + w2[n] * acc[ai][0][m][n];
; #pragma unroll
;                     for (int e = 0; e < 4; ++e) { const float x = c[e]; const float uu = 0.7978845608028654f * (x + 0.044715f * x * x * x);
;                         const float gl = x * __builtin_amdgcn_rcpf(1.f + __builtin_amdgcn_exp2f(-2.885390081777927f * uu)); o[n][e] = gl * acc[ai][1][m][n][e]; } }
;                 const int row = u.pm * BM + ai * HALF + wr * 64 + m * 16 + fr;
;                 if (!(m == 0 && fr < 2)) *(u32x4*)(G + (size_t)row * DFF + f0) = pack8(o[0], o[1]);
;                 if (m == 0 && fr < 2) { float* ah = AH + ((size_t)jb * 4 + 2 + fr) * DFF + f0; *(f32x4*)ah = acc[ai][0][0][0]; *(f32x4*)(ah + 4) = acc[ai][0][0][1];
;                     float* bh = BH + ((size_t)jb * 2 + fr) * DFF + f0; *(f32x4*)bh = acc[ai][1][0][0]; *(f32x4*)(bh + 4) = acc[ai][1][0][1]; }
;                 if (m == 3 && fr >= 14) { float* ah = AH + ((size_t)jb * 4 + (fr - 14)) * DFF + f0; *(f32x4*)ah = acc[ai][0][3][0]; *(f32x4*)(ah + 4) = acc[ai][0][3][1]; }
	v_cndmask_b32_e64 v137, v153, v141, s[8:9]
	v_mul_f32_e32 v134, 0x3d372713, v125
	v_mul_f32_e32 v134, v125, v134
	v_mul_f32_e32 v135, 0x3d372713, v124
	v_fma_f32 v134, v125, v134, v125
	v_mul_f32_e32 v135, v124, v135
	v_fma_f32 v135, v124, v135, v124
	v_mul_f32_e32 v134, 0xc0135761, v134
	v_exp_f32_e32 v134, v134
	v_mul_f32_e32 v135, 0xc0135761, v135
	v_exp_f32_e32 v136, v135
	ds_bpermute_b32 v143, v213, v128
	v_add_f32_e32 v134, 1.0, v134
	v_rcp_f32_e32 v135, v134
	v_add_f32_e32 v134, 1.0, v136
	v_rcp_f32_e32 v134, v134
	v_cndmask_b32_e64 v136, v151, v139, s[8:9]
	v_pk_fma_f32 v[136:137], v[98:99], v[136:137], v[110:111]
	ds_bpermute_b32 v149, v213, v129
	v_pk_mul_f32 v[124:125], v[124:125], v[134:135]
	s_waitcnt lgkmcnt(2)
	v_cndmask_b32_e64 v135, v140, v152, s[0:1]
	v_cndmask_b32_e64 v134, v138, v150, s[0:1]
	v_pk_fma_f32 v[134:135], v[102:103], v[134:135], v[136:137]
	ds_bpermute_b32 v142, v212, v128
	v_pk_fma_f32 v[126:127], v[126:127], v[106:107], v[134:135]
	ds_bpermute_b32 v144, v212, v129
	v_mul_f32_e32 v134, 0x3d372713, v126
	v_mul_f32_e32 v135, 0x3d372713, v127
	v_mul_f32_e32 v134, v126, v134
	v_mul_f32_e32 v135, v127, v135
	v_fma_f32 v134, v126, v134, v126
	v_fma_f32 v135, v127, v135, v127
	v_mul_f32_e32 v134, 0xc0135761, v134
	v_mul_f32_e32 v135, 0xc0135761, v135
	v_exp_f32_e32 v134, v134
	v_exp_f32_e32 v135, v135
	s_waitcnt lgkmcnt(2)
	v_cndmask_b32_e64 v137, v161, v149, s[8:9]
	v_cndmask_b32_e64 v136, v155, v143, s[8:9]
	v_pk_mul_f32 v[124:125], v[116:117], v[124:125]
	v_add_f32_e32 v116, 1.0, v134
	v_add_f32_e32 v117, 1.0, v135
	s_waitcnt lgkmcnt(0)
	v_cndmask_b32_e64 v135, v144, v156, s[0:1]
	v_cndmask_b32_e64 v134, v142, v154, s[0:1]
	v_pk_fma_f32 v[136:137], v[100:101], v[136:137], v[112:113]
	ds_bpermute_b32 v158, v213, v122
	v_pk_fma_f32 v[134:135], v[104:105], v[134:135], v[136:137]
	ds_bpermute_b32 v160, v213, v123
	v_pk_fma_f32 v[128:129], v[128:129], v[108:109], v[134:135]
	ds_bpermute_b32 v157, v212, v122
	v_mul_f32_e32 v134, 0x3d372713, v128
	v_mul_f32_e32 v135, 0x3d372713, v129
	v_mul_f32_e32 v134, v128, v134
	v_mul_f32_e32 v135, v129, v135
	v_fma_f32 v134, v128, v134, v128
	v_fma_f32 v135, v129, v135, v129
	ds_bpermute_b32 v159, v212, v123
	v_mul_f32_e32 v134, 0xc0135761, v134
	v_mul_f32_e32 v135, 0xc0135761, v135
	v_rcp_f32_e32 v116, v116
	v_rcp_f32_e32 v117, v117
	v_exp_f32_e32 v134, v134
	v_exp_f32_e32 v135, v135
	s_waitcnt lgkmcnt(2)
	v_cndmask_b32_e64 v137, v205, v160, s[8:9]
	v_cndmask_b32_e64 v136, v203, v158, s[8:9]
	v_pk_mul_f32 v[116:117], v[126:127], v[116:117]
	v_add_f32_e32 v126, 1.0, v134
	v_add_f32_e32 v127, 1.0, v135
	s_waitcnt lgkmcnt(0)
	v_cndmask_b32_e64 v135, v159, v204, s[0:1]
	v_cndmask_b32_e64 v134, v157, v202, s[0:1]
	v_pk_fma_f32 v[136:137], v[82:83], v[136:137], v[94:95]
	v_rcp_f32_e32 v126, v126
	v_pk_fma_f32 v[134:135], v[86:87], v[134:135], v[136:137]
	v_rcp_f32_e32 v127, v127
	v_pk_fma_f32 v[122:123], v[122:123], v[90:91], v[134:135]
	v_pk_mul_f32 v[116:117], v[118:119], v[116:117]
	v_mul_f32_e32 v134, 0x3d372713, v123
	v_mul_f32_e32 v134, v123, v134
	v_mul_f32_e32 v135, 0x3d372713, v122
	v_fma_f32 v134, v123, v134, v123
	v_mul_f32_e32 v135, v122, v135
	v_fma_f32 v135, v122, v135, v122
	v_mul_f32_e32 v134, 0xc0135761, v134
	v_exp_f32_e32 v134, v134
	v_mul_f32_e32 v135, 0xc0135761, v135
	v_exp_f32_e32 v136, v135
	v_pk_mul_f32 v[118:119], v[128:129], v[126:127]
	v_add_f32_e32 v134, 1.0, v134
	v_rcp_f32_e32 v135, v134
	v_add_f32_e32 v134, 1.0, v136
	v_rcp_f32_e32 v134, v134
	v_pk_mul_f32 v[118:119], v[120:121], v[118:119]
	ds_bpermute_b32 v126, v213, v81
	ds_bpermute_b32 v129, v213, v71
	v_pk_mul_f32 v[120:121], v[122:123], v[134:135]
	v_or_b32_e32 v122, 32, v215
	v_pk_mul_f32 v[120:121], v[114:115], v[120:121]
	v_cvt_pk_bf16_f32 v115, v118, v119
	v_mad_i64_i32 v[118:119], s[70:71], v122, s79, v[132:133]
	v_cvt_pk_bf16_f32 v114, v116, v117
	v_cvt_pk_bf16_f32 v116, v120, v121
	v_cvt_pk_bf16_f32 v117, v124, v125
	v_lshl_add_u64 v[118:119], v[118:119], 0, v[130:131]
	global_store_dwordx4 v[118:119], v[114:117], off
	ds_bpermute_b32 v114, v212, v73
	ds_bpermute_b32 v116, v212, v72
	ds_bpermute_b32 v117, v213, v73
	ds_bpermute_b32 v125, v213, v72
	ds_bpermute_b32 v118, v212, v78
	s_waitcnt lgkmcnt(4)
	v_cndmask_b32_e64 v115, v114, v145, s[0:1]
	s_waitcnt lgkmcnt(3)
	v_cndmask_b32_e64 v114, v116, v146, s[0:1]
	s_waitcnt lgkmcnt(2)
	v_cndmask_b32_e64 v117, v147, v117, s[8:9]
	s_waitcnt lgkmcnt(1)
	v_cndmask_b32_e64 v116, v148, v125, s[8:9]
	v_pk_fma_f32 v[116:117], v[84:85], v[116:117], v[96:97]
	ds_bpermute_b32 v120, v213, v78
	v_pk_fma_f32 v[114:115], v[88:89], v[114:115], v[116:117]
	ds_bpermute_b32 v119, v212, v79
	v_pk_fma_f32 v[114:115], v[72:73], v[92:93], v[114:115]
	ds_bpermute_b32 v121, v213, v79
	v_mul_f32_e32 v116, 0x3d372713, v115
	v_mul_f32_e32 v116, v115, v116
	v_mul_f32_e32 v117, 0x3d372713, v114
	v_fma_f32 v116, v115, v116, v115
	v_mul_f32_e32 v117, v114, v117
	v_fma_f32 v117, v114, v117, v114
	v_mul_f32_e32 v116, 0xc0135761, v116
	v_exp_f32_e32 v116, v116
	v_mul_f32_e32 v117, 0xc0135761, v117
	v_exp_f32_e32 v125, v117
	ds_bpermute_b32 v123, v213, v80
	v_add_f32_e32 v116, 1.0, v116
	v_rcp_f32_e32 v117, v116
	v_add_f32_e32 v116, 1.0, v125
	v_rcp_f32_e32 v116, v116
	ds_bpermute_b32 v122, v212, v80
	ds_bpermute_b32 v124, v212, v81
	ds_bpermute_b32 v125, v213, v70
	v_pk_mul_f32 v[114:115], v[114:115], v[116:117]
	s_waitcnt lgkmcnt(5)
	v_cndmask_b32_e64 v117, v119, v140, s[0:1]
	v_cndmask_b32_e64 v116, v118, v138, s[0:1]
	s_waitcnt lgkmcnt(4)
; __device__ __forceinline__ u32x4 pack8(const f32x4 a, const f32x4 b) { u32x4 w; w.x = cvt_pk_bf16(a[0], a[1]); w.y = cvt_pk_bf16(a[2], a[3]); w.z = cvt_pk_bf16(b[0], b[1]); w.w = cvt_pk_bf16(b[2], b[3]); return w; }
;     __device__ __forceinline__ void operator()(const f32x4 (&acc)[2][2][4][2], const Unit& u, int wr, int wc, int fr, int fq) const {
;     ...
;                 for (int n = 0; n < 2; ++n) { f32x4 r1, r2;
; #pragma unroll
;                     for (int e = 0; e < 4; ++e) { const float a0 = acc[ai][0][m][n][e]; r1[e] = __shfl(a0, src1); r2[e] = __shfl(a0, src2); }
;                     f32x4 a1, a2;
; #pragma unroll
;                     for (int e = 0; e < 4; ++e) { a1[e] = fr >= 1 ? r1[e] : p1[n][e]; a2[e] = fr >= 2 ? r2[e] : p2[n][e]; }
;                     p1[n] = r1; p2[n] = r2;
;                     const f32x4 c = bb[n] + w0[n] * a2 + w1[n] * a1 + w2[n] * acc[ai][0][m][n];
; #pragma unroll
;                     for (int e = 0; e < 4; ++e) { const float x = c[e]; const float uu = 0.7978845608028654f * (x + 0.044715f * x * x * x);
;                         const float gl = x * __builtin_amdgcn_rcpf(1.f + __builtin_amdgcn_exp2f(-2.885390081777927f * uu)); o[n][e] = gl * acc[ai][1][m][n][e]; } }
;                 const int row = u.pm * BM + ai * HALF + wr * 64 + m * 16 + fr;
;                 if (!(m == 0 && fr < 2)) *(u32x4*)(G + (size_t)row * DFF + f0) = pack8(o[0], o[1]);
;                 if (m == 0 && fr < 2) { float* ah = AH + ((size_t)jb * 4 + 2 + fr) * DFF + f0; *(f32x4*)ah = acc[ai][0][0][0]; *(f32x4*)(ah + 4) = acc[ai][0][0][1];
;                     float* bh = BH + ((size_t)jb * 2 + fr) * DFF + f0; *(f32x4*)bh = acc[ai][1][0][0]; *(f32x4*)(bh + 4) = acc[ai][1][0][1]; }
;                 if (m == 3 && fr >= 14) { float* ah = AH + ((size_t)jb * 4 + (fr - 14)) * DFF + f0; *(f32x4*)ah = acc[ai][0][3][0]; *(f32x4*)(ah + 4) = acc[ai][0][3][1]; }
	v_cndmask_b32_e64 v119, v141, v121, s[8:9]
	v_cndmask_b32_e64 v118, v139, v120, s[8:9]
	v_pk_fma_f32 v[118:119], v[98:99], v[118:119], v[110:111]
	v_cndmask_b32_e64 v121, v149, v126, s[8:9]
	v_pk_fma_f32 v[116:117], v[102:103], v[116:117], v[118:119]
	s_waitcnt lgkmcnt(3)
	v_cndmask_b32_e64 v120, v143, v123, s[8:9]
	v_pk_fma_f32 v[116:117], v[78:79], v[106:107], v[116:117]
	v_pk_mul_f32 v[114:115], v[68:69], v[114:115]
	v_mul_f32_e32 v118, 0x3d372713, v116
	v_mul_f32_e32 v119, 0x3d372713, v117
	v_mul_f32_e32 v118, v116, v118
	v_mul_f32_e32 v119, v117, v119
	v_fma_f32 v118, v116, v118, v116
	v_fma_f32 v119, v117, v119, v117
	v_mul_f32_e32 v118, 0xc0135761, v118
	v_mul_f32_e32 v119, 0xc0135761, v119
	v_exp_f32_e32 v118, v118
	v_exp_f32_e32 v119, v119
	v_pk_fma_f32 v[120:121], v[100:101], v[120:121], v[112:113]
	ds_bpermute_b32 v127, v212, v70
	v_add_f32_e32 v68, 1.0, v118
	v_add_f32_e32 v69, 1.0, v119
	s_waitcnt lgkmcnt(2)
	v_cndmask_b32_e64 v119, v124, v144, s[0:1]
	v_cndmask_b32_e64 v118, v122, v142, s[0:1]
	v_pk_fma_f32 v[118:119], v[104:105], v[118:119], v[120:121]
	ds_bpermute_b32 v128, v212, v71
	v_pk_fma_f32 v[118:119], v[80:81], v[108:109], v[118:119]
	v_rcp_f32_e32 v68, v68
	v_mul_f32_e32 v120, 0x3d372713, v118
	v_mul_f32_e32 v121, 0x3d372713, v119
	v_mul_f32_e32 v120, v118, v120
	v_mul_f32_e32 v121, v119, v121
	v_fma_f32 v120, v118, v120, v118
	v_fma_f32 v121, v119, v121, v119
	v_mul_f32_e32 v120, 0xc0135761, v120
	v_mul_f32_e32 v121, 0xc0135761, v121
	v_rcp_f32_e32 v69, v69
	v_exp_f32_e32 v120, v120
	v_exp_f32_e32 v121, v121
	v_cndmask_b32_e64 v123, v160, v129, s[8:9]
	s_waitcnt lgkmcnt(2)
	v_cndmask_b32_e64 v122, v158, v125, s[8:9]
	v_pk_mul_f32 v[68:69], v[116:117], v[68:69]
	v_add_f32_e32 v116, 1.0, v120
	v_add_f32_e32 v117, 1.0, v121
	s_waitcnt lgkmcnt(0)
	v_cndmask_b32_e64 v121, v128, v159, s[0:1]
	v_cndmask_b32_e64 v120, v127, v157, s[0:1]
	v_pk_fma_f32 v[122:123], v[82:83], v[122:123], v[94:95]
	v_rcp_f32_e32 v116, v116
	v_pk_fma_f32 v[120:121], v[86:87], v[120:121], v[122:123]
	v_rcp_f32_e32 v117, v117
	v_pk_fma_f32 v[120:121], v[70:71], v[90:91], v[120:121]
	v_pk_mul_f32 v[68:69], v[74:75], v[68:69]
	v_mul_f32_e32 v122, 0x3d372713, v121
	v_mul_f32_e32 v122, v121, v122
	v_mul_f32_e32 v123, 0x3d372713, v120
	v_fma_f32 v122, v121, v122, v121
	v_mul_f32_e32 v123, v120, v123
	v_fma_f32 v123, v120, v123, v120
	v_mul_f32_e32 v122, 0xc0135761, v122
	v_exp_f32_e32 v122, v122
	v_mul_f32_e32 v123, 0xc0135761, v123
	v_exp_f32_e32 v124, v123
	v_pk_mul_f32 v[74:75], v[118:119], v[116:117]
	v_add_f32_e32 v122, 1.0, v122
	v_rcp_f32_e32 v123, v122
	v_add_f32_e32 v122, 1.0, v124
	v_rcp_f32_e32 v122, v122
	v_pk_mul_f32 v[74:75], v[76:77], v[74:75]
	v_or_b32_e32 v116, 48, v215
	v_pk_mul_f32 v[76:77], v[120:121], v[122:123]
	s_nop 0
	v_pk_mul_f32 v[76:77], v[66:67], v[76:77]
	v_cvt_pk_bf16_f32 v67, v74, v75
	v_mad_i64_i32 v[74:75], s[70:71], v116, s79, v[132:133]
	v_cvt_pk_bf16_f32 v66, v68, v69
	v_cvt_pk_bf16_f32 v68, v76, v77
	v_cvt_pk_bf16_f32 v69, v114, v115
	v_lshl_add_u64 v[74:75], v[74:75], 0, v[130:131]
	global_store_dwordx4 v[74:75], v[66:69], off
	s_and_saveexec_b64 s[70:71], s[4:5]
	s_cbranch_execz .LBB0_917
	v_lshl_add_u64 v[66:67], s[68:69], 0, v[176:177]
	v_mov_b64_e32 v[68:69], s[14:15]
	v_mad_u64_u32 v[68:69], s[68:69], v66, s80, v[68:69]
	v_mad_i32_i24 v69, v67, s80, v69
	v_lshl_add_u64 v[66:67], v[186:187], 2, v[68:69]
	global_store_dwordx4 v[66:67], v[78:81], off
	global_store_dwordx4 v[66:67], v[70:73], off offset:16
; __device__ __forceinline__ u32x4 pack8(const f32x4 a, const f32x4 b) { u32x4 w; w.x = cvt_pk_bf16(a[0], a[1]); w.y = cvt_pk_bf16(a[2], a[3]); w.z = cvt_pk_bf16(b[0], b[1]); w.w = cvt_pk_bf16(b[2], b[3]); return w; }
;     __device__ __forceinline__ void operator()(const f32x4 (&acc)[2][2][4][2], const Unit& u, int wr, int wc, int fr, int fq) const {
;     ...
;                 for (int n = 0; n < 2; ++n) { f32x4 r1, r2;
; #pragma unroll
;                     for (int e = 0; e < 4; ++e) { const float a0 = acc[ai][0][m][n][e]; r1[e] = __shfl(a0, src1); r2[e] = __shfl(a0, src2); }
;                     f32x4 a1, a2;
; #pragma unroll
;                     for (int e = 0; e < 4; ++e) { a1[e] = fr >= 1 ? r1[e] : p1[n][e]; a2[e] = fr >= 2 ? r2[e] : p2[n][e]; }
;                     p1[n] = r1; p2[n] = r2;
;                     const f32x4 c = bb[n] + w0[n] * a2 + w1[n] * a1 + w2[n] * acc[ai][0][m][n];
; #pragma unroll
;                     for (int e = 0; e < 4; ++e) { const float x = c[e]; const float uu = 0.7978845608028654f * (x + 0.044715f * x * x * x);
;                         const float gl = x * __builtin_amdgcn_rcpf(1.f + __builtin_amdgcn_exp2f(-2.885390081777927f * uu)); o[n][e] = gl * acc[ai][1][m][n][e]; } }
;                 const int row = u.pm * BM + ai * HALF + wr * 64 + m * 16 + fr;
;                 if (!(m == 0 && fr < 2)) *(u32x4*)(G + (size_t)row * DFF + f0) = pack8(o[0], o[1]);
;                 if (m == 0 && fr < 2) { float* ah = AH + ((size_t)jb * 4 + 2 + fr) * DFF + f0; *(f32x4*)ah = acc[ai][0][0][0]; *(f32x4*)(ah + 4) = acc[ai][0][0][1];
;                     float* bh = BH + ((size_t)jb * 2 + fr) * DFF + f0; *(f32x4*)bh = acc[ai][1][0][0]; *(f32x4*)(bh + 4) = acc[ai][1][0][1]; }
;                 if (m == 3 && fr >= 14) { float* ah = AH + ((size_t)jb * 4 + (fr - 14)) * DFF + f0; *(f32x4*)ah = acc[ai][0][3][0]; *(f32x4*)(ah + 4) = acc[ai][0][3][1]; }
.LBB0_917:
	s_or_b64 exec, exec, s[70:71]
	ds_bpermute_b32 v76, v212, v62
	ds_bpermute_b32 v74, v213, v62
	ds_bpermute_b32 v77, v212, v63
	ds_bpermute_b32 v75, v213, v63
	ds_bpermute_b32 v72, v212, v64
	ds_bpermute_b32 v70, v213, v64
	ds_bpermute_b32 v73, v212, v65
	ds_bpermute_b32 v71, v213, v65
	ds_bpermute_b32 v68, v212, v58
	ds_bpermute_b32 v66, v213, v58
	ds_bpermute_b32 v69, v212, v59
	ds_bpermute_b32 v67, v213, v59
	ds_bpermute_b32 v80, v212, v60
	ds_bpermute_b32 v78, v213, v60
	ds_bpermute_b32 v81, v212, v61
	ds_bpermute_b32 v79, v213, v61
	s_and_saveexec_b64 s[68:69], s[8:9]
	s_xor_b64 s[68:69], exec, s[68:69]
	s_cbranch_execz .LBB0_919
	s_waitcnt lgkmcnt(0)
	v_pk_fma_f32 v[114:115], v[84:85], v[78:79], v[96:97]
	s_nop 0
	v_pk_fma_f32 v[114:115], v[88:89], v[80:81], v[114:115]
	s_nop 0
	v_pk_fma_f32 v[114:115], v[60:61], v[92:93], v[114:115]
	s_nop 0
	v_mul_f32_e32 v116, 0x3d372713, v115
	v_mul_f32_e32 v116, v115, v116
	v_mul_f32_e32 v117, 0x3d372713, v114
	v_fma_f32 v116, v115, v116, v115
	v_mul_f32_e32 v117, v114, v117
	v_fma_f32 v117, v114, v117, v114
	v_mul_f32_e32 v116, 0xc0135761, v116
	v_exp_f32_e32 v116, v116
	v_mul_f32_e32 v117, 0xc0135761, v117
	v_exp_f32_e32 v118, v117
	v_add_f32_e32 v116, 1.0, v116
	v_rcp_f32_e32 v117, v116
	v_add_f32_e32 v116, 1.0, v118
	v_rcp_f32_e32 v116, v116
	s_nop 0
	v_pk_mul_f32 v[114:115], v[114:115], v[116:117]
	v_pk_fma_f32 v[116:117], v[98:99], v[74:75], v[110:111]
	s_nop 0
	v_pk_fma_f32 v[116:117], v[102:103], v[76:77], v[116:117]
	s_nop 0
	v_pk_fma_f32 v[116:117], v[62:63], v[106:107], v[116:117]
	s_nop 0
	v_mul_f32_e32 v118, 0x3d372713, v116
	v_mul_f32_e32 v118, v116, v118
	v_fma_f32 v118, v116, v118, v116
	v_mul_f32_e32 v118, 0xc0135761, v118
	v_exp_f32_e32 v120, v118
	v_mul_f32_e32 v118, 0x3d372713, v117
	v_mul_f32_e32 v118, v117, v118
	v_fma_f32 v118, v117, v118, v117
	v_mul_f32_e32 v118, 0xc0135761, v118
	v_exp_f32_e32 v121, v118
	v_pk_mul_f32 v[118:119], v[52:53], v[114:115]
	v_add_f32_e32 v114, 1.0, v120
	v_rcp_f32_e32 v114, v114
	v_add_f32_e32 v115, 1.0, v121
	v_pk_fma_f32 v[120:121], v[100:101], v[70:71], v[112:113]
	v_rcp_f32_e32 v115, v115
	v_pk_fma_f32 v[120:121], v[104:105], v[72:73], v[120:121]
	v_pk_mul_f32 v[114:115], v[116:117], v[114:115]
	v_pk_fma_f32 v[120:121], v[64:65], v[108:109], v[120:121]
	v_pk_mul_f32 v[114:115], v[54:55], v[114:115]
	v_mul_f32_e32 v122, 0x3d372713, v120
	v_mul_f32_e32 v123, 0x3d372713, v121
	v_mul_f32_e32 v122, v120, v122
	v_mul_f32_e32 v123, v121, v123
	v_fma_f32 v122, v120, v122, v120
	v_fma_f32 v123, v121, v123, v121
	v_mul_f32_e32 v122, 0xc0135761, v122
	v_mul_f32_e32 v123, 0xc0135761, v123
	v_exp_f32_e32 v122, v122
	v_exp_f32_e32 v123, v123
	v_cvt_pk_bf16_f32 v114, v114, v115
	v_add_f32_e32 v116, 1.0, v122
	v_add_f32_e32 v117, 1.0, v123
	v_pk_fma_f32 v[122:123], v[82:83], v[66:67], v[94:95]
	v_rcp_f32_e32 v116, v116
	v_pk_fma_f32 v[122:123], v[86:87], v[68:69], v[122:123]
	v_rcp_f32_e32 v117, v117
	v_pk_fma_f32 v[122:123], v[58:59], v[90:91], v[122:123]
	v_pk_mul_f32 v[116:117], v[120:121], v[116:117]
	v_mul_f32_e32 v124, 0x3d372713, v123
	v_mul_f32_e32 v124, v123, v124
	v_mul_f32_e32 v125, 0x3d372713, v122
	v_fma_f32 v124, v123, v124, v123
	v_mul_f32_e32 v125, v122, v125
	v_fma_f32 v125, v122, v125, v122
	v_mul_f32_e32 v124, 0xc0135761, v124
	v_exp_f32_e32 v124, v124
	v_mul_f32_e32 v125, 0xc0135761, v125
	v_exp_f32_e32 v126, v125
	v_pk_mul_f32 v[116:117], v[56:57], v[116:117]
	v_add_f32_e32 v124, 1.0, v124
	v_rcp_f32_e32 v125, v124
	v_add_f32_e32 v124, 1.0, v126
	v_rcp_f32_e32 v124, v124
	v_cvt_pk_bf16_f32 v115, v116, v117
	v_cvt_pk_bf16_f32 v117, v118, v119
	v_mov_b64_e32 v[118:119], s[10:11]
	v_pk_mul_f32 v[120:121], v[122:123], v[124:125]
	v_add_u32_e32 v122, 0x80, v215
	v_pk_mul_f32 v[120:121], v[50:51], v[120:121]
	v_mad_i64_i32 v[118:119], s[70:71], v122, s79, v[118:119]
	v_cvt_pk_bf16_f32 v116, v120, v121
	v_lshl_add_u64 v[118:119], v[186:187], 1, v[118:119]
	global_store_dwordx4 v[118:119], v[114:117], off

; __device__ __forceinline__ u32x4 pack8(const f32x4 a, const f32x4 b) { u32x4 w; w.x = cvt_pk_bf16(a[0], a[1]); w.y = cvt_pk_bf16(a[2], a[3]); w.z = cvt_pk_bf16(b[0], b[1]); w.w = cvt_pk_bf16(b[2], b[3]); return w; }
;     __device__ __forceinline__ void operator()(const f32x4 (&acc)[2][2][4][2], const Unit& u, int wr, int wc, int fr, int fq) const {
;     ...
;                 for (int n = 0; n < 2; ++n) { f32x4 r1, r2;
; #pragma unroll
;                     for (int e = 0; e < 4; ++e) { const float a0 = acc[ai][0][m][n][e]; r1[e] = __shfl(a0, src1); r2[e] = __shfl(a0, src2); }
;                     f32x4 a1, a2;
; #pragma unroll
;                     for (int e = 0; e < 4; ++e) { a1[e] = fr >= 1 ? r1[e] : p1[n][e]; a2[e] = fr >= 2 ? r2[e] : p2[n][e]; }
;                     p1[n] = r1; p2[n] = r2;
;                     const f32x4 c = bb[n] + w0[n] * a2 + w1[n] * a1 + w2[n] * acc[ai][0][m][n];
; #pragma unroll
;                     for (int e = 0; e < 4; ++e) { const float x = c[e]; const float uu = 0.7978845608028654f * (x + 0.044715f * x * x * x);
;                         const float gl = x * __builtin_amdgcn_rcpf(1.f + __builtin_amdgcn_exp2f(-2.885390081777927f * uu)); o[n][e] = gl * acc[ai][1][m][n][e]; } }
;                 const int row = u.pm * BM + ai * HALF + wr * 64 + m * 16 + fr;
;                 if (!(m == 0 && fr < 2)) *(u32x4*)(G + (size_t)row * DFF + f0) = pack8(o[0], o[1]);
.LBB0_921:
	s_or_b64 exec, exec, s[68:69]
	ds_bpermute_b32 v63, v213, v45
	ds_bpermute_b32 v64, v213, v44
	ds_bpermute_b32 v61, v212, v45
	ds_bpermute_b32 v62, v212, v44
	ds_bpermute_b32 v55, v213, v46
	s_waitcnt lgkmcnt(4)
	v_cndmask_b32_e64 v53, v79, v63, s[8:9]
	s_waitcnt lgkmcnt(3)
	v_cndmask_b32_e64 v52, v78, v64, s[8:9]
	s_waitcnt lgkmcnt(2)
	v_cndmask_b32_e64 v51, v61, v81, s[0:1]
	s_waitcnt lgkmcnt(1)
	v_cndmask_b32_e64 v50, v62, v80, s[0:1]
	v_pk_fma_f32 v[52:53], v[84:85], v[52:53], v[96:97]
	ds_bpermute_b32 v57, v213, v47
	v_pk_fma_f32 v[50:51], v[88:89], v[50:51], v[52:53]
	ds_bpermute_b32 v54, v212, v46
	v_pk_fma_f32 v[44:45], v[44:45], v[92:93], v[50:51]
	ds_bpermute_b32 v56, v212, v47
	v_mul_f32_e32 v50, 0x3d372713, v45
	v_mul_f32_e32 v50, v45, v50
	v_mul_f32_e32 v51, 0x3d372713, v44
	v_fma_f32 v50, v45, v50, v45
	v_mul_f32_e32 v51, v44, v51
	v_fma_f32 v51, v44, v51, v44
	v_mul_f32_e32 v50, 0xc0135761, v50
	v_exp_f32_e32 v50, v50
	v_mul_f32_e32 v51, 0xc0135761, v51
	v_exp_f32_e32 v52, v51
	s_waitcnt lgkmcnt(2)
	v_cndmask_b32_e64 v53, v75, v57, s[8:9]
	v_add_f32_e32 v50, 1.0, v50
	v_rcp_f32_e32 v51, v50
	v_add_f32_e32 v50, 1.0, v52
	v_rcp_f32_e32 v50, v50
	v_cndmask_b32_e64 v52, v74, v55, s[8:9]
	v_pk_fma_f32 v[52:53], v[98:99], v[52:53], v[110:111]
	ds_bpermute_b32 v59, v213, v48
	v_pk_mul_f32 v[44:45], v[44:45], v[50:51]
	s_waitcnt lgkmcnt(1)
	v_cndmask_b32_e64 v51, v56, v77, s[0:1]
	v_cndmask_b32_e64 v50, v54, v76, s[0:1]
	v_pk_fma_f32 v[50:51], v[102:103], v[50:51], v[52:53]
	ds_bpermute_b32 v65, v213, v49
	v_pk_fma_f32 v[46:47], v[46:47], v[106:107], v[50:51]
	ds_bpermute_b32 v58, v212, v48
	v_mul_f32_e32 v50, 0x3d372713, v46
	v_mul_f32_e32 v51, 0x3d372713, v47
	v_mul_f32_e32 v50, v46, v50
	v_mul_f32_e32 v51, v47, v51
	v_fma_f32 v50, v46, v50, v46
	v_fma_f32 v51, v47, v51, v47
	ds_bpermute_b32 v60, v212, v49
	v_mul_f32_e32 v50, 0xc0135761, v50
	v_mul_f32_e32 v51, 0xc0135761, v51
	v_exp_f32_e32 v50, v50
	v_exp_f32_e32 v51, v51
	s_waitcnt lgkmcnt(2)
	v_cndmask_b32_e64 v53, v71, v65, s[8:9]
	v_cndmask_b32_e64 v52, v70, v59, s[8:9]
	v_pk_mul_f32 v[44:45], v[36:37], v[44:45]
	v_add_f32_e32 v36, 1.0, v50
	v_add_f32_e32 v37, 1.0, v51
	s_waitcnt lgkmcnt(0)
	v_cndmask_b32_e64 v51, v60, v73, s[0:1]
	v_cndmask_b32_e64 v50, v58, v72, s[0:1]
	v_pk_fma_f32 v[52:53], v[100:101], v[52:53], v[112:113]
	ds_bpermute_b32 v79, v213, v42
	v_pk_fma_f32 v[50:51], v[104:105], v[50:51], v[52:53]
	ds_bpermute_b32 v81, v213, v43
	v_pk_fma_f32 v[48:49], v[48:49], v[108:109], v[50:51]
	ds_bpermute_b32 v78, v212, v42
	v_mul_f32_e32 v50, 0x3d372713, v48
	v_mul_f32_e32 v51, 0x3d372713, v49
	v_mul_f32_e32 v50, v48, v50
	v_mul_f32_e32 v51, v49, v51
	v_fma_f32 v50, v48, v50, v48
	v_fma_f32 v51, v49, v51, v49
	ds_bpermute_b32 v80, v212, v43
	v_mul_f32_e32 v50, 0xc0135761, v50
	v_mul_f32_e32 v51, 0xc0135761, v51
	v_rcp_f32_e32 v36, v36
	v_rcp_f32_e32 v37, v37
	v_exp_f32_e32 v50, v50
	v_exp_f32_e32 v51, v51
	s_waitcnt lgkmcnt(2)
	v_cndmask_b32_e64 v53, v67, v81, s[8:9]
	v_cndmask_b32_e64 v52, v66, v79, s[8:9]
	v_pk_mul_f32 v[36:37], v[46:47], v[36:37]
	v_add_f32_e32 v46, 1.0, v50
	v_add_f32_e32 v47, 1.0, v51
	s_waitcnt lgkmcnt(0)
	v_cndmask_b32_e64 v51, v80, v69, s[0:1]
	v_cndmask_b32_e64 v50, v78, v68, s[0:1]
	v_pk_fma_f32 v[52:53], v[82:83], v[52:53], v[94:95]
	v_rcp_f32_e32 v46, v46
	v_pk_fma_f32 v[50:51], v[86:87], v[50:51], v[52:53]
	v_rcp_f32_e32 v47, v47
	v_pk_fma_f32 v[42:43], v[42:43], v[90:91], v[50:51]
	v_pk_mul_f32 v[36:37], v[38:39], v[36:37]
	v_mul_f32_e32 v50, 0x3d372713, v43
	v_mul_f32_e32 v50, v43, v50
	v_mul_f32_e32 v51, 0x3d372713, v42
	v_fma_f32 v50, v43, v50, v43
	v_mul_f32_e32 v51, v42, v51
	v_fma_f32 v51, v42, v51, v42
	v_mul_f32_e32 v50, 0xc0135761, v50
	v_exp_f32_e32 v50, v50
	v_mul_f32_e32 v51, 0xc0135761, v51
	v_exp_f32_e32 v52, v51
	v_pk_mul_f32 v[38:39], v[48:49], v[46:47]
	v_add_f32_e32 v50, 1.0, v50
	v_rcp_f32_e32 v51, v50
	v_add_f32_e32 v50, 1.0, v52
	v_rcp_f32_e32 v50, v50
	v_pk_mul_f32 v[38:39], v[40:41], v[38:39]
	ds_bpermute_b32 v49, v213, v29
	ds_bpermute_b32 v47, v212, v29
	v_pk_mul_f32 v[40:41], v[42:43], v[50:51]
	ds_bpermute_b32 v50, v213, v28
	v_pk_mul_f32 v[34:35], v[34:35], v[40:41]
	ds_bpermute_b32 v48, v212, v28
	v_add_u32_e32 v40, 0x90, v215
	v_cvt_pk_bf16_f32 v36, v36, v37
	v_cvt_pk_bf16_f32 v37, v38, v39
	v_cvt_pk_bf16_f32 v38, v34, v35
	v_mov_b64_e32 v[34:35], s[10:11]
	v_mad_i64_i32 v[40:41], s[68:69], v40, s79, v[34:35]
	v_cvt_pk_bf16_f32 v39, v44, v45
	v_lshl_add_u64 v[40:41], v[40:41], 0, v[130:131]
	global_store_dwordx4 v[40:41], v[36:39], off
	ds_bpermute_b32 v41, v213, v30
	ds_bpermute_b32 v43, v213, v31
	s_waitcnt lgkmcnt(5)
	v_cndmask_b32_e64 v39, v63, v49, s[8:9]
	s_waitcnt lgkmcnt(3)
	v_cndmask_b32_e64 v38, v64, v50, s[8:9]
	v_cndmask_b32_e64 v37, v47, v61, s[0:1]
	s_waitcnt lgkmcnt(2)
	v_cndmask_b32_e64 v36, v48, v62, s[0:1]
	v_pk_fma_f32 v[38:39], v[84:85], v[38:39], v[96:97]
	ds_bpermute_b32 v40, v212, v30
	v_pk_fma_f32 v[36:37], v[88:89], v[36:37], v[38:39]
	ds_bpermute_b32 v42, v212, v31
	v_pk_fma_f32 v[28:29], v[28:29], v[92:93], v[36:37]
	s_waitcnt lgkmcnt(2)
	v_cndmask_b32_e64 v39, v57, v43, s[8:9]
	v_mul_f32_e32 v36, 0x3d372713, v29
	v_mul_f32_e32 v36, v29, v36
	v_mul_f32_e32 v37, 0x3d372713, v28
	v_fma_f32 v36, v29, v36, v29
	v_mul_f32_e32 v37, v28, v37
	v_fma_f32 v37, v28, v37, v28
	v_mul_f32_e32 v36, 0xc0135761, v36
	v_exp_f32_e32 v36, v36
	v_mul_f32_e32 v37, 0xc0135761, v37
	v_exp_f32_e32 v38, v37
	ds_bpermute_b32 v45, v213, v32
	v_add_f32_e32 v36, 1.0, v36
	v_rcp_f32_e32 v37, v36
	v_add_f32_e32 v36, 1.0, v38
	v_rcp_f32_e32 v36, v36
	v_cndmask_b32_e64 v38, v55, v41, s[8:9]
	v_pk_fma_f32 v[38:39], v[98:99], v[38:39], v[110:111]
	ds_bpermute_b32 v51, v213, v33
	v_pk_mul_f32 v[28:29], v[28:29], v[36:37]
	s_waitcnt lgkmcnt(2)
; __device__ __forceinline__ u32x4 pack8(const f32x4 a, const f32x4 b) { u32x4 w; w.x = cvt_pk_bf16(a[0], a[1]); w.y = cvt_pk_bf16(a[2], a[3]); w.z = cvt_pk_bf16(b[0], b[1]); w.w = cvt_pk_bf16(b[2], b[3]); return w; }
;     __device__ __forceinline__ void operator()(const f32x4 (&acc)[2][2][4][2], const Unit& u, int wr, int wc, int fr, int fq) const {
;     ...
;                 for (int n = 0; n < 2; ++n) { f32x4 r1, r2;
; #pragma unroll
;                     for (int e = 0; e < 4; ++e) { const float a0 = acc[ai][0][m][n][e]; r1[e] = __shfl(a0, src1); r2[e] = __shfl(a0, src2); }
;                     f32x4 a1, a2;
; #pragma unroll
;                     for (int e = 0; e < 4; ++e) { a1[e] = fr >= 1 ? r1[e] : p1[n][e]; a2[e] = fr >= 2 ? r2[e] : p2[n][e]; }
;                     p1[n] = r1; p2[n] = r2;
;                     const f32x4 c = bb[n] + w0[n] * a2 + w1[n] * a1 + w2[n] * acc[ai][0][m][n];
; #pragma unroll
;                     for (int e = 0; e < 4; ++e) { const float x = c[e]; const float uu = 0.7978845608028654f * (x + 0.044715f * x * x * x);
;                         const float gl = x * __builtin_amdgcn_rcpf(1.f + __builtin_amdgcn_exp2f(-2.885390081777927f * uu)); o[n][e] = gl * acc[ai][1][m][n][e]; } }
;                 const int row = u.pm * BM + ai * HALF + wr * 64 + m * 16 + fr;
;                 if (!(m == 0 && fr < 2)) *(u32x4*)(G + (size_t)row * DFF + f0) = pack8(o[0], o[1]);
	v_cndmask_b32_e64 v37, v42, v56, s[0:1]
	v_cndmask_b32_e64 v36, v40, v54, s[0:1]
	v_pk_fma_f32 v[36:37], v[102:103], v[36:37], v[38:39]
	ds_bpermute_b32 v44, v212, v32
	v_pk_fma_f32 v[30:31], v[30:31], v[106:107], v[36:37]
	ds_bpermute_b32 v46, v212, v33
	v_mul_f32_e32 v36, 0x3d372713, v30
	v_mul_f32_e32 v37, 0x3d372713, v31
	v_mul_f32_e32 v36, v30, v36
	v_mul_f32_e32 v37, v31, v37
	v_fma_f32 v36, v30, v36, v30
	v_fma_f32 v37, v31, v37, v31
	v_mul_f32_e32 v36, 0xc0135761, v36
	v_mul_f32_e32 v37, 0xc0135761, v37
	v_exp_f32_e32 v36, v36
	v_exp_f32_e32 v37, v37
	s_waitcnt lgkmcnt(2)
	v_cndmask_b32_e64 v39, v65, v51, s[8:9]
	v_cndmask_b32_e64 v38, v59, v45, s[8:9]
	v_pk_mul_f32 v[28:29], v[20:21], v[28:29]
	v_add_f32_e32 v20, 1.0, v36
	v_add_f32_e32 v21, 1.0, v37
	s_waitcnt lgkmcnt(0)
	v_cndmask_b32_e64 v37, v46, v60, s[0:1]
	v_cndmask_b32_e64 v36, v44, v58, s[0:1]
	v_pk_fma_f32 v[38:39], v[100:101], v[38:39], v[112:113]
	ds_bpermute_b32 v53, v213, v26
	v_pk_fma_f32 v[36:37], v[104:105], v[36:37], v[38:39]
	ds_bpermute_b32 v62, v213, v27
	v_pk_fma_f32 v[32:33], v[32:33], v[108:109], v[36:37]
	ds_bpermute_b32 v52, v212, v26
	v_mul_f32_e32 v36, 0x3d372713, v32
	v_mul_f32_e32 v37, 0x3d372713, v33
	v_mul_f32_e32 v36, v32, v36
	v_mul_f32_e32 v37, v33, v37
	v_fma_f32 v36, v32, v36, v32
	v_fma_f32 v37, v33, v37, v33
	ds_bpermute_b32 v61, v212, v27
	v_mul_f32_e32 v36, 0xc0135761, v36
	v_mul_f32_e32 v37, 0xc0135761, v37
	v_rcp_f32_e32 v20, v20
	v_rcp_f32_e32 v21, v21
	v_exp_f32_e32 v36, v36
	v_exp_f32_e32 v37, v37
	s_waitcnt lgkmcnt(2)
	v_cndmask_b32_e64 v39, v81, v62, s[8:9]
	v_cndmask_b32_e64 v38, v79, v53, s[8:9]
	v_pk_mul_f32 v[20:21], v[30:31], v[20:21]
	v_add_f32_e32 v30, 1.0, v36
	v_add_f32_e32 v31, 1.0, v37
	s_waitcnt lgkmcnt(0)
	v_cndmask_b32_e64 v37, v61, v80, s[0:1]
	v_cndmask_b32_e64 v36, v52, v78, s[0:1]
	v_pk_fma_f32 v[38:39], v[82:83], v[38:39], v[94:95]
	v_rcp_f32_e32 v30, v30
	v_pk_fma_f32 v[36:37], v[86:87], v[36:37], v[38:39]
	v_rcp_f32_e32 v31, v31
	v_pk_fma_f32 v[26:27], v[26:27], v[90:91], v[36:37]
	v_pk_mul_f32 v[20:21], v[22:23], v[20:21]
	v_mul_f32_e32 v36, 0x3d372713, v27
	v_mul_f32_e32 v36, v27, v36
	v_mul_f32_e32 v37, 0x3d372713, v26
	v_fma_f32 v36, v27, v36, v27
	v_mul_f32_e32 v37, v26, v37
	v_fma_f32 v37, v26, v37, v26
	v_mul_f32_e32 v36, 0xc0135761, v36
	v_exp_f32_e32 v36, v36
	v_mul_f32_e32 v37, 0xc0135761, v37
	v_exp_f32_e32 v38, v37
	v_pk_mul_f32 v[22:23], v[32:33], v[30:31]
	v_add_f32_e32 v36, 1.0, v36
	v_rcp_f32_e32 v37, v36
	v_add_f32_e32 v36, 1.0, v38
	v_rcp_f32_e32 v36, v36
	v_pk_mul_f32 v[22:23], v[24:25], v[22:23]
	ds_bpermute_b32 v31, v213, v8
	ds_bpermute_b32 v33, v213, v9
	v_pk_mul_f32 v[24:25], v[26:27], v[36:37]
	v_add_u32_e32 v26, 0xa0, v215
	v_pk_mul_f32 v[24:25], v[18:19], v[24:25]
	v_cvt_pk_bf16_f32 v19, v22, v23
	v_mad_i64_i32 v[22:23], s[68:69], v26, s79, v[34:35]
	v_cvt_pk_bf16_f32 v18, v20, v21
	v_cvt_pk_bf16_f32 v20, v24, v25
	v_cvt_pk_bf16_f32 v21, v28, v29
	v_lshl_add_u64 v[22:23], v[22:23], 0, v[130:131]
	global_store_dwordx4 v[22:23], v[18:21], off
	ds_bpermute_b32 v20, v213, v10
	ds_bpermute_b32 v21, v213, v11
	ds_bpermute_b32 v18, v212, v10
	ds_bpermute_b32 v19, v212, v11
	ds_bpermute_b32 v22, v212, v12
	s_waitcnt lgkmcnt(4)
	v_cndmask_b32_e64 v20, v41, v20, s[8:9]
	s_waitcnt lgkmcnt(3)
	v_cndmask_b32_e64 v21, v43, v21, s[8:9]
	s_waitcnt lgkmcnt(2)
	v_cndmask_b32_e64 v18, v18, v40, s[0:1]
	s_waitcnt lgkmcnt(1)
; __device__ __forceinline__ u32x4 pack8(const f32x4 a, const f32x4 b) { u32x4 w; w.x = cvt_pk_bf16(a[0], a[1]); w.y = cvt_pk_bf16(a[2], a[3]); w.z = cvt_pk_bf16(b[0], b[1]); w.w = cvt_pk_bf16(b[2], b[3]); return w; }
;     __device__ __forceinline__ void operator()(const f32x4 (&acc)[2][2][4][2], const Unit& u, int wr, int wc, int fr, int fq) const {
;     ...
;                 for (int n = 0; n < 2; ++n) { f32x4 r1, r2;
; #pragma unroll
;                     for (int e = 0; e < 4; ++e) { const float a0 = acc[ai][0][m][n][e]; r1[e] = __shfl(a0, src1); r2[e] = __shfl(a0, src2); }
;                     f32x4 a1, a2;
; #pragma unroll
;                     for (int e = 0; e < 4; ++e) { a1[e] = fr >= 1 ? r1[e] : p1[n][e]; a2[e] = fr >= 2 ? r2[e] : p2[n][e]; }
;                     p1[n] = r1; p2[n] = r2;
;                     const f32x4 c = bb[n] + w0[n] * a2 + w1[n] * a1 + w2[n] * acc[ai][0][m][n];
; #pragma unroll
;                     for (int e = 0; e < 4; ++e) { const float x = c[e]; const float uu = 0.7978845608028654f * (x + 0.044715f * x * x * x);
;                         const float gl = x * __builtin_amdgcn_rcpf(1.f + __builtin_amdgcn_exp2f(-2.885390081777927f * uu)); o[n][e] = gl * acc[ai][1][m][n][e]; } }
;                 const int row = u.pm * BM + ai * HALF + wr * 64 + m * 16 + fr;
;                 if (!(m == 0 && fr < 2)) *(u32x4*)(G + (size_t)row * DFF + f0) = pack8(o[0], o[1]);
;                 if (m == 0 && fr < 2) { float* ah = AH + ((size_t)jb * 4 + 2 + fr) * DFF + f0; *(f32x4*)ah = acc[ai][0][0][0]; *(f32x4*)(ah + 4) = acc[ai][0][0][1];
;                     float* bh = BH + ((size_t)jb * 2 + fr) * DFF + f0; *(f32x4*)bh = acc[ai][1][0][0]; *(f32x4*)(bh + 4) = acc[ai][1][0][1]; }
;                 if (m == 3 && fr >= 14) { float* ah = AH + ((size_t)jb * 4 + (fr - 14)) * DFF + f0; *(f32x4*)ah = acc[ai][0][3][0]; *(f32x4*)(ah + 4) = acc[ai][0][3][1]; }
	v_cndmask_b32_e64 v19, v19, v42, s[0:1]
	v_pk_fma_f32 v[20:21], v[98:99], v[20:21], v[110:111]
	ds_bpermute_b32 v24, v213, v12
	v_pk_fma_f32 v[18:19], v[102:103], v[18:19], v[20:21]
	ds_bpermute_b32 v23, v212, v13
	v_pk_fma_f32 v[18:19], v[10:11], v[106:107], v[18:19]
	ds_bpermute_b32 v25, v213, v13
	v_mul_f32_e32 v20, 0x3d372713, v18
	v_mul_f32_e32 v21, 0x3d372713, v19
	v_mul_f32_e32 v20, v18, v20
	v_mul_f32_e32 v21, v19, v21
	v_fma_f32 v20, v18, v20, v18
	v_fma_f32 v21, v19, v21, v19
	v_mul_f32_e32 v20, 0xc0135761, v20
	v_mul_f32_e32 v21, 0xc0135761, v21
	v_exp_f32_e32 v20, v20
	v_exp_f32_e32 v21, v21
	ds_bpermute_b32 v27, v213, v6
	ds_bpermute_b32 v29, v213, v7
	v_add_f32_e32 v20, 1.0, v20
	v_add_f32_e32 v21, 1.0, v21
	v_rcp_f32_e32 v20, v20
	v_rcp_f32_e32 v21, v21
	ds_bpermute_b32 v26, v212, v6
	ds_bpermute_b32 v28, v212, v7
	ds_bpermute_b32 v30, v212, v8
	v_pk_mul_f32 v[18:19], v[18:19], v[20:21]
	s_waitcnt lgkmcnt(6)
	v_cndmask_b32_e64 v21, v23, v46, s[0:1]
	v_cndmask_b32_e64 v20, v22, v44, s[0:1]
	s_waitcnt lgkmcnt(5)
	v_cndmask_b32_e64 v23, v51, v25, s[8:9]
	v_cndmask_b32_e64 v22, v45, v24, s[8:9]
	v_pk_fma_f32 v[22:23], v[100:101], v[22:23], v[112:113]
	s_waitcnt lgkmcnt(3)
	v_cndmask_b32_e64 v25, v62, v29, s[8:9]
	v_pk_fma_f32 v[20:21], v[104:105], v[20:21], v[22:23]
	v_cndmask_b32_e64 v24, v53, v27, s[8:9]
	v_pk_fma_f32 v[20:21], v[12:13], v[108:109], v[20:21]
	v_pk_mul_f32 v[14:15], v[14:15], v[18:19]
	v_mul_f32_e32 v22, 0x3d372713, v20
	v_mul_f32_e32 v23, 0x3d372713, v21
	v_mul_f32_e32 v22, v20, v22
	v_mul_f32_e32 v23, v21, v23
	v_fma_f32 v22, v20, v22, v20
	v_fma_f32 v23, v21, v23, v21
	v_mul_f32_e32 v22, 0xc0135761, v22
	v_mul_f32_e32 v23, 0xc0135761, v23
	v_exp_f32_e32 v22, v22
	v_exp_f32_e32 v23, v23
	v_pk_fma_f32 v[24:25], v[82:83], v[24:25], v[94:95]
	ds_bpermute_b32 v32, v212, v9
	v_add_f32_e32 v18, 1.0, v22
	v_add_f32_e32 v19, 1.0, v23
	s_waitcnt lgkmcnt(2)
	v_cndmask_b32_e64 v23, v28, v61, s[0:1]
	v_cndmask_b32_e64 v22, v26, v52, s[0:1]
	v_pk_fma_f32 v[22:23], v[86:87], v[22:23], v[24:25]
	v_rcp_f32_e32 v18, v18
	v_pk_fma_f32 v[22:23], v[6:7], v[90:91], v[22:23]
	v_rcp_f32_e32 v19, v19
	v_mul_f32_e32 v24, 0x3d372713, v22
	v_mul_f32_e32 v25, 0x3d372713, v23
	v_mul_f32_e32 v24, v22, v24
	v_mul_f32_e32 v25, v23, v25
	v_fma_f32 v24, v22, v24, v22
	v_fma_f32 v25, v23, v25, v23
	v_mul_f32_e32 v24, 0xc0135761, v24
	v_mul_f32_e32 v25, 0xc0135761, v25
	v_exp_f32_e32 v24, v24
	v_exp_f32_e32 v25, v25
	v_cndmask_b32_e64 v27, v49, v33, s[8:9]
	v_cndmask_b32_e64 v26, v50, v31, s[8:9]
	v_pk_mul_f32 v[18:19], v[20:21], v[18:19]
	v_add_f32_e32 v20, 1.0, v24
	v_add_f32_e32 v21, 1.0, v25
	s_waitcnt lgkmcnt(0)
	v_cndmask_b32_e64 v25, v32, v47, s[0:1]
	v_cndmask_b32_e64 v24, v30, v48, s[0:1]
	v_pk_fma_f32 v[26:27], v[84:85], v[26:27], v[96:97]
	v_rcp_f32_e32 v20, v20
	v_pk_fma_f32 v[24:25], v[88:89], v[24:25], v[26:27]
	v_rcp_f32_e32 v21, v21
	v_pk_fma_f32 v[24:25], v[8:9], v[92:93], v[24:25]
	v_pk_mul_f32 v[16:17], v[16:17], v[18:19]
	v_mul_f32_e32 v26, 0x3d372713, v25
	v_mul_f32_e32 v26, v25, v26
	v_mul_f32_e32 v27, 0x3d372713, v24
	v_fma_f32 v26, v25, v26, v25
	v_mul_f32_e32 v27, v24, v27
	v_fma_f32 v27, v24, v27, v24
	v_mul_f32_e32 v26, 0xc0135761, v26
	v_exp_f32_e32 v26, v26
	v_mul_f32_e32 v27, 0xc0135761, v27
	v_exp_f32_e32 v28, v27
	v_pk_mul_f32 v[18:19], v[22:23], v[20:21]
	v_add_f32_e32 v26, 1.0, v26
	v_rcp_f32_e32 v27, v26
	v_add_f32_e32 v26, 1.0, v28
	v_rcp_f32_e32 v26, v26
	v_pk_mul_f32 v[18:19], v[2:3], v[18:19]
	v_add_u32_e32 v22, 0xb0, v215
	v_pk_mul_f32 v[2:3], v[24:25], v[26:27]
	s_nop 0
	v_pk_mul_f32 v[20:21], v[4:5], v[2:3]
	v_cvt_pk_bf16_f32 v2, v14, v15
	v_mad_i64_i32 v[14:15], s[68:69], v22, s79, v[34:35]
	v_cvt_pk_bf16_f32 v3, v16, v17
	v_cvt_pk_bf16_f32 v4, v18, v19
	v_cvt_pk_bf16_f32 v5, v20, v21
	v_lshl_add_u64 v[14:15], v[14:15], 0, v[130:131]
	global_store_dwordx4 v[14:15], v[2:5], off
	s_and_saveexec_b64 s[68:69], s[4:5]
	s_cbranch_execz .LBB0_923
	v_lshl_add_u64 v[2:3], s[66:67], 0, v[176:177]
	v_mov_b64_e32 v[4:5], s[14:15]
	v_mad_u64_u32 v[4:5], s[66:67], v2, s80, v[4:5]
	v_mad_i32_i24 v5, v3, s80, v5
	v_lshl_add_u64 v[2:3], v[186:187], 2, v[4:5]
	global_store_dwordx4 v[2:3], v[10:13], off
	global_store_dwordx4 v[2:3], v[6:9], off offset:16

; __device__ __forceinline__ unsigned pk2(float lo, float hi) { return f2bf(lo) | (f2bf(hi) << 16); }
; __global__ void __launch_bounds__(512) fwd_mega(Args a) {
;     ...
;             const f32x4 c = *(const f32x4*)(a.conv_b + f) + *(const f32x4*)(a.conv_w + f) * a2 + *(const f32x4*)(a.conv_w + DFF + f) * a1 + *(const f32x4*)(a.conv_w + 2 * DFF + f) * a0;
;             float o[4];
; #pragma unroll
;             for (int e = 0; e < 4; ++e) { const float x = c[e]; const float uu = 0.7978845608028654f * (x + 0.044715f * x * x * x);
;                 o[e] = x * __builtin_amdgcn_rcpf(1.f + __builtin_amdgcn_exp2f(-2.885390081777927f * uu)) * bv[e]; }
;             *(unsigned long long*)(GG + ((size_t)jb * 64 + ii) * DFF + f) = (unsigned long long)pk2(o[0], o[1]) | ((unsigned long long)pk2(o[2], o[3]) << 32); }
.Lp9_z0b:
	v_pk_fma_f32 v[16:17], v[20:21], v[32:33], v[16:17]
	v_pk_fma_f32 v[18:19], v[22:23], v[34:35], v[18:19]
	v_pk_fma_f32 v[16:17], v[24:25], v[36:37], v[16:17]
	v_pk_fma_f32 v[18:19], v[26:27], v[38:39], v[18:19]
	v_pk_fma_f32 v[16:17], v[28:29], v[40:41], v[16:17]
	v_pk_fma_f32 v[18:19], v[30:31], v[42:43], v[18:19]
	v_mul_f32_e32 v20, 0x3d372713, v16
	v_mul_f32_e32 v21, 0x3d372713, v17
	v_mul_f32_e32 v22, 0x3d372713, v18
	v_mul_f32_e32 v23, 0x3d372713, v19
	v_mul_f32_e32 v20, v16, v20
	v_mul_f32_e32 v21, v17, v21
	v_mul_f32_e32 v22, v18, v22
	v_mul_f32_e32 v23, v19, v23
	v_fma_f32 v20, v16, v20, v16
	v_fma_f32 v21, v17, v21, v17
	v_fma_f32 v22, v18, v22, v18
	v_fma_f32 v23, v19, v23, v19
	v_mul_f32_e32 v20, 0xc0135761, v20
	v_mul_f32_e32 v21, 0xc0135761, v21
	v_mul_f32_e32 v22, 0xc0135761, v22
	v_mul_f32_e32 v23, 0xc0135761, v23
	v_exp_f32_e32 v20, v20
	v_exp_f32_e32 v21, v21
	v_exp_f32_e32 v22, v22
	v_exp_f32_e32 v23, v23
	s_nop 0
	v_add_f32_e32 v20, 1.0, v20
	v_add_f32_e32 v21, 1.0, v21
	v_add_f32_e32 v22, 1.0, v22
	v_add_f32_e32 v23, 1.0, v23
	v_rcp_f32_e32 v20, v20
	v_rcp_f32_e32 v21, v21
	v_rcp_f32_e32 v22, v22
	v_rcp_f32_e32 v23, v23
	s_nop 0
	v_pk_mul_f32 v[16:17], v[16:17], v[20:21]
	v_pk_mul_f32 v[18:19], v[18:19], v[22:23]
	v_pk_mul_f32 v[16:17], v[44:45], v[16:17]
	v_pk_mul_f32 v[18:19], v[46:47], v[18:19]
	v_cvt_pk_bf16_f32 v16, v16, v17
	v_cvt_pk_bf16_f32 v17, v18, v19
	global_store_dwordx2 v144, v[16:17], s[52:53]
	v_readlane_b32 s36, v4, 2
	v_readlane_b32 s37, v4, 3
	s_nop 3
	s_cmp_eq_u32 s36, 0
	s_cbranch_scc1 .Lp9_z1a
	v_mov_b32_e32 v64, 0
	v_mov_b32_e32 v65, 0
	v_mov_b32_e32 v66, 0
	v_mov_b32_e32 v67, 0

; __device__ __forceinline__ unsigned pk2(float lo, float hi) { return f2bf(lo) | (f2bf(hi) << 16); }
; __global__ void __launch_bounds__(512) fwd_mega(Args a) {
;     ...
;             const f32x4 c = *(const f32x4*)(a.conv_b + f) + *(const f32x4*)(a.conv_w + f) * a2 + *(const f32x4*)(a.conv_w + DFF + f) * a1 + *(const f32x4*)(a.conv_w + 2 * DFF + f) * a0;
;             float o[4];
; #pragma unroll
;             for (int e = 0; e < 4; ++e) { const float x = c[e]; const float uu = 0.7978845608028654f * (x + 0.044715f * x * x * x);
;                 o[e] = x * __builtin_amdgcn_rcpf(1.f + __builtin_amdgcn_exp2f(-2.885390081777927f * uu)) * bv[e]; }
;             *(unsigned long long*)(GG + ((size_t)jb * 64 + ii) * DFF + f) = (unsigned long long)pk2(o[0], o[1]) | ((unsigned long long)pk2(o[2], o[3]) << 32); }
.Lp9_z1b:
	v_pk_fma_f32 v[48:49], v[52:53], v[64:65], v[48:49]
	v_pk_fma_f32 v[50:51], v[54:55], v[66:67], v[50:51]
	v_pk_fma_f32 v[48:49], v[56:57], v[68:69], v[48:49]
	v_pk_fma_f32 v[50:51], v[58:59], v[70:71], v[50:51]
	v_pk_fma_f32 v[48:49], v[60:61], v[72:73], v[48:49]
	v_pk_fma_f32 v[50:51], v[62:63], v[74:75], v[50:51]
	v_mul_f32_e32 v52, 0x3d372713, v48
	v_mul_f32_e32 v53, 0x3d372713, v49
	v_mul_f32_e32 v54, 0x3d372713, v50
	v_mul_f32_e32 v55, 0x3d372713, v51
	v_mul_f32_e32 v52, v48, v52
	v_mul_f32_e32 v53, v49, v53
	v_mul_f32_e32 v54, v50, v54
	v_mul_f32_e32 v55, v51, v55
	v_fma_f32 v52, v48, v52, v48
	v_fma_f32 v53, v49, v53, v49
	v_fma_f32 v54, v50, v54, v50
	v_fma_f32 v55, v51, v55, v51
	v_mul_f32_e32 v52, 0xc0135761, v52
	v_mul_f32_e32 v53, 0xc0135761, v53
	v_mul_f32_e32 v54, 0xc0135761, v54
	v_mul_f32_e32 v55, 0xc0135761, v55
	v_exp_f32_e32 v52, v52
	v_exp_f32_e32 v53, v53
	v_exp_f32_e32 v54, v54
	v_exp_f32_e32 v55, v55
	s_nop 0
	v_add_f32_e32 v52, 1.0, v52
	v_add_f32_e32 v53, 1.0, v53
	v_add_f32_e32 v54, 1.0, v54
	v_add_f32_e32 v55, 1.0, v55
	v_rcp_f32_e32 v52, v52
	v_rcp_f32_e32 v53, v53
	v_rcp_f32_e32 v54, v54
	v_rcp_f32_e32 v55, v55
	s_nop 0
	v_pk_mul_f32 v[48:49], v[48:49], v[52:53]
	v_pk_mul_f32 v[50:51], v[50:51], v[54:55]
	v_pk_mul_f32 v[48:49], v[76:77], v[48:49]
	v_pk_mul_f32 v[50:51], v[78:79], v[50:51]
	v_cvt_pk_bf16_f32 v48, v48, v49
	v_cvt_pk_bf16_f32 v49, v50, v51
	global_store_dwordx2 v145, v[48:49], s[52:53]
	v_readlane_b32 s36, v4, 4
	v_readlane_b32 s37, v4, 5
	s_nop 3
	s_cmp_eq_u32 s36, 0
	s_cbranch_scc1 .Lp9_z2a
	v_mov_b32_e32 v96, 0
	v_mov_b32_e32 v97, 0
	v_mov_b32_e32 v98, 0
	v_mov_b32_e32 v99, 0

; __device__ __forceinline__ unsigned pk2(float lo, float hi) { return f2bf(lo) | (f2bf(hi) << 16); }
; __global__ void __launch_bounds__(512) fwd_mega(Args a) {
;     ...
;             const f32x4 c = *(const f32x4*)(a.conv_b + f) + *(const f32x4*)(a.conv_w + f) * a2 + *(const f32x4*)(a.conv_w + DFF + f) * a1 + *(const f32x4*)(a.conv_w + 2 * DFF + f) * a0;
;             float o[4];
; #pragma unroll
;             for (int e = 0; e < 4; ++e) { const float x = c[e]; const float uu = 0.7978845608028654f * (x + 0.044715f * x * x * x);
;                 o[e] = x * __builtin_amdgcn_rcpf(1.f + __builtin_amdgcn_exp2f(-2.885390081777927f * uu)) * bv[e]; }
;             *(unsigned long long*)(GG + ((size_t)jb * 64 + ii) * DFF + f) = (unsigned long long)pk2(o[0], o[1]) | ((unsigned long long)pk2(o[2], o[3]) << 32); }
.Lp9_z2b:
	v_pk_fma_f32 v[80:81], v[84:85], v[96:97], v[80:81]
	v_pk_fma_f32 v[82:83], v[86:87], v[98:99], v[82:83]
	v_pk_fma_f32 v[80:81], v[88:89], v[100:101], v[80:81]
	v_pk_fma_f32 v[82:83], v[90:91], v[102:103], v[82:83]
	v_pk_fma_f32 v[80:81], v[92:93], v[104:105], v[80:81]
	v_pk_fma_f32 v[82:83], v[94:95], v[106:107], v[82:83]
	v_mul_f32_e32 v84, 0x3d372713, v80
	v_mul_f32_e32 v85, 0x3d372713, v81
	v_mul_f32_e32 v86, 0x3d372713, v82
	v_mul_f32_e32 v87, 0x3d372713, v83
	v_mul_f32_e32 v84, v80, v84
	v_mul_f32_e32 v85, v81, v85
	v_mul_f32_e32 v86, v82, v86
	v_mul_f32_e32 v87, v83, v87
	v_fma_f32 v84, v80, v84, v80
	v_fma_f32 v85, v81, v85, v81
	v_fma_f32 v86, v82, v86, v82
	v_fma_f32 v87, v83, v87, v83
	v_mul_f32_e32 v84, 0xc0135761, v84
	v_mul_f32_e32 v85, 0xc0135761, v85
	v_mul_f32_e32 v86, 0xc0135761, v86
	v_mul_f32_e32 v87, 0xc0135761, v87
	v_exp_f32_e32 v84, v84
	v_exp_f32_e32 v85, v85
	v_exp_f32_e32 v86, v86
	v_exp_f32_e32 v87, v87
	s_nop 0
	v_add_f32_e32 v84, 1.0, v84
	v_add_f32_e32 v85, 1.0, v85
	v_add_f32_e32 v86, 1.0, v86
	v_add_f32_e32 v87, 1.0, v87
	v_rcp_f32_e32 v84, v84
	v_rcp_f32_e32 v85, v85
	v_rcp_f32_e32 v86, v86
	v_rcp_f32_e32 v87, v87
	s_nop 0
	v_pk_mul_f32 v[80:81], v[80:81], v[84:85]
	v_pk_mul_f32 v[82:83], v[82:83], v[86:87]
	v_pk_mul_f32 v[80:81], v[108:109], v[80:81]
	v_pk_mul_f32 v[82:83], v[110:111], v[82:83]
	v_cvt_pk_bf16_f32 v80, v80, v81
	v_cvt_pk_bf16_f32 v81, v82, v83
	global_store_dwordx2 v146, v[80:81], s[52:53]
	v_readlane_b32 s36, v4, 6
	v_readlane_b32 s37, v4, 7
	s_nop 3
	s_cmp_eq_u32 s36, 0
	s_cbranch_scc1 .Lp9_z3a
	v_mov_b32_e32 v128, 0
	v_mov_b32_e32 v129, 0
	v_mov_b32_e32 v130, 0
	v_mov_b32_e32 v131, 0

; __device__ __forceinline__ unsigned pk2(float lo, float hi) { return f2bf(lo) | (f2bf(hi) << 16); }
; __global__ void __launch_bounds__(512) fwd_mega(Args a) {
;     ...
;             const f32x4 c = *(const f32x4*)(a.conv_b + f) + *(const f32x4*)(a.conv_w + f) * a2 + *(const f32x4*)(a.conv_w + DFF + f) * a1 + *(const f32x4*)(a.conv_w + 2 * DFF + f) * a0;
;             float o[4];
; #pragma unroll
;             for (int e = 0; e < 4; ++e) { const float x = c[e]; const float uu = 0.7978845608028654f * (x + 0.044715f * x * x * x);
;                 o[e] = x * __builtin_amdgcn_rcpf(1.f + __builtin_amdgcn_exp2f(-2.885390081777927f * uu)) * bv[e]; }
;             *(unsigned long long*)(GG + ((size_t)jb * 64 + ii) * DFF + f) = (unsigned long long)pk2(o[0], o[1]) | ((unsigned long long)pk2(o[2], o[3]) << 32); }
.Lp9_z3b:
	v_pk_fma_f32 v[112:113], v[116:117], v[128:129], v[112:113]
	v_pk_fma_f32 v[114:115], v[118:119], v[130:131], v[114:115]
	v_pk_fma_f32 v[112:113], v[120:121], v[132:133], v[112:113]
	v_pk_fma_f32 v[114:115], v[122:123], v[134:135], v[114:115]
	v_pk_fma_f32 v[112:113], v[124:125], v[136:137], v[112:113]
	v_pk_fma_f32 v[114:115], v[126:127], v[138:139], v[114:115]
	v_mul_f32_e32 v116, 0x3d372713, v112
	v_mul_f32_e32 v117, 0x3d372713, v113
	v_mul_f32_e32 v118, 0x3d372713, v114
	v_mul_f32_e32 v119, 0x3d372713, v115
	v_mul_f32_e32 v116, v112, v116
	v_mul_f32_e32 v117, v113, v117
	v_mul_f32_e32 v118, v114, v118
	v_mul_f32_e32 v119, v115, v119
	v_fma_f32 v116, v112, v116, v112
	v_fma_f32 v117, v113, v117, v113
	v_fma_f32 v118, v114, v118, v114
	v_fma_f32 v119, v115, v119, v115
	v_mul_f32_e32 v116, 0xc0135761, v116
	v_mul_f32_e32 v117, 0xc0135761, v117
	v_mul_f32_e32 v118, 0xc0135761, v118
	v_mul_f32_e32 v119, 0xc0135761, v119
	v_exp_f32_e32 v116, v116
	v_exp_f32_e32 v117, v117
	v_exp_f32_e32 v118, v118
	v_exp_f32_e32 v119, v119
	s_nop 0
	v_add_f32_e32 v116, 1.0, v116
	v_add_f32_e32 v117, 1.0, v117
	v_add_f32_e32 v118, 1.0, v118
	v_add_f32_e32 v119, 1.0, v119
	v_rcp_f32_e32 v116, v116
	v_rcp_f32_e32 v117, v117
	v_rcp_f32_e32 v118, v118
	v_rcp_f32_e32 v119, v119
	s_nop 0
	v_pk_mul_f32 v[112:113], v[112:113], v[116:117]
	v_pk_mul_f32 v[114:115], v[114:115], v[118:119]
	v_pk_mul_f32 v[112:113], v[140:141], v[112:113]
	v_pk_mul_f32 v[114:115], v[142:143], v[114:115]
	v_cvt_pk_bf16_f32 v112, v112, v113
	v_cvt_pk_bf16_f32 v113, v114, v115
	global_store_dwordx2 v147, v[112:113], s[52:53]
	s_lshl_b32 s36, s16, 2
	s_add_u32 s2, s2, s36
	s_cmp_lt_u32 s2, 1441792
	s_cbranch_scc1 .Lp9_batch
